# E1 L0+L2 converted to swapped-MFMA layout: mode 0 dwordx2 coalesced stores (no LDS transpose), mode 3 transposed store via ds_write_b64 tile with full-line stores
# baseline (speedup 1.0000x reference)
; __device__ __forceinline__ unsigned xb_ld(unsigned* p)              { return __hip_atomic_load(p, __ATOMIC_RELAXED, __HIP_MEMORY_SCOPE_AGENT); }
; #define PP load_params()
; #define FRESH_IDS() int tid = threadIdx.x; asm volatile("" : "+v"(tid)); const int lane = tid & 63, wave = tid >> 6; \
;     const int gw = blockIdx.x * 8 + wave, gtid = blockIdx.x * 512 + tid; LAS float* scr = (LAS float*)(lds + wave * 16896); (void)lane; (void)gw; (void)gtid; (void)scr;
; template <int layer>
; __device__ __forceinline__ void run_layer(LAS unsigned char* lds, const XcdBarrier& xb) {
;     unsigned char* ws = PP.ws;
;     const int G = gridDim.x, NGW = G * 8, NT = G * 512;
;     bf16_t* XB = (bf16_t*)(ws + OFF_XB); float* RSS = (float*)(ws + OFF_RSS);
;     bf16_t* WIN = (bf16_t*)(ws + OFF_WIN); bf16_t* WOUT = (bf16_t*)(ws + OFF_WOUT);
;     (void)NGW; (void)NT; (void)XB; (void)RSS; (void)WIN; (void)WOUT;
;         const int li = layer >> 1;
;         const bool last_layer = (layer == 3);
;         if ((layer & 1) == 0) {
;             if (layer > 0) { FRESH_IDS(); wconv<0>(PP.w_out_e + (size_t)li * 2048 * 2048, 2048, WOUT, nullptr, scr, gw, NGW, lane); }
;             __syncthreads();
;             { pg8::GemmSched S; S.init(T, 5120, G, blockIdx.x, XB, 2048, WIN, 2048); EpiIn<false> E{RSS, ws}; pg8::gemm_phase(lds, 2048, 2048, 2048, S, E); }
; __global__ void __launch_bounds__(512, 2) hybrid_fwd(Params p) {
;     ...
;     { unsigned mine = 0u, cnt = 0u;
; #pragma unroll
;       for (unsigned j = 0; j < 16; ++j) { const unsigned c = xb_ld(&xb.bar[XB_XCNT(j)]); cnt += (c > 0u) ? 1u : 0u; mine = (j == xb.x) ? c : mine; }
;       xb.nloc = __builtin_amdgcn_readfirstlane(mine > 0u ? mine : 1u); xb.nx = __builtin_amdgcn_readfirstlane(cnt > 0u ? cnt : 1u); }
.LBB0_200:
	s_or_b64 exec, exec, s[4:5]
	v_mov_b32_e32 v0, 0x180000
	s_barrier
	global_load_dword v1, v0, s[86:87] offset:1024 sc1
	global_load_dword v2, v0, s[86:87] offset:1280 sc1
	global_load_dword v3, v0, s[86:87] offset:1536 sc1
	v_mov_b32_e32 v4, 0x181000
	global_load_dword v5, v0, s[86:87] offset:1792 sc1
	global_load_dword v6, v0, s[86:87] offset:2048 sc1
	global_load_dword v7, v0, s[86:87] offset:2304 sc1
	global_load_dword v8, v0, s[86:87] offset:2560 sc1
	global_load_dword v9, v0, s[86:87] offset:2816 sc1
	global_load_dword v10, v0, s[86:87] offset:3072 sc1
	global_load_dword v11, v0, s[86:87] offset:3328 sc1
	global_load_dword v12, v0, s[86:87] offset:3584 sc1
	global_load_dword v13, v0, s[86:87] offset:3840 sc1
	global_load_dword v14, v4, s[86:87] sc1
	global_load_dword v15, v4, s[86:87] offset:256 sc1
	global_load_dword v16, v4, s[86:87] offset:512 sc1
	s_cmp_eq_u32 s73, 0
	global_load_dword v0, v4, s[86:87] offset:768 sc1
	s_cselect_b64 vcc, -1, 0
	s_cmp_eq_u32 s73, 1
	s_mov_b64 s[0:1], s[74:75]
	s_load_dwordx2 s[36:37], s[0:1], 0x90
	s_waitcnt lgkmcnt(0)
	s_barrier
	s_waitcnt vmcnt(15)
	v_cndmask_b32_e32 v4, 0, v1, vcc
	s_waitcnt vmcnt(14)
	v_cmp_ne_u32_e32 vcc, 0, v2
	s_waitcnt vmcnt(13)
	v_cmp_ne_u32_e64 s[4:5], 0, v3
	v_cndmask_b32_e64 v17, 0, 1, vcc
	s_nop 0
	v_cndmask_b32_e64 v18, 0, 1, s[4:5]
	s_waitcnt vmcnt(11)
	v_cmp_ne_u32_e64 s[4:5], 0, v6
	s_cselect_b64 vcc, -1, 0
	s_cmp_eq_u32 s73, 2
	v_cndmask_b32_e64 v19, 0, 1, s[4:5]
	s_waitcnt vmcnt(9)
	v_cmp_ne_u32_e64 s[4:5], 0, v8
	v_cndmask_b32_e32 v2, v4, v2, vcc
	s_cselect_b64 vcc, -1, 0
	v_cndmask_b32_e64 v20, 0, 1, s[4:5]
	s_waitcnt vmcnt(7)
	v_cmp_ne_u32_e64 s[4:5], 0, v10
	v_cndmask_b32_e32 v2, v2, v3, vcc
	v_cmp_ne_u32_e32 vcc, 0, v5
	v_cndmask_b32_e64 v21, 0, 1, s[4:5]
	s_waitcnt vmcnt(5)
	v_cmp_ne_u32_e64 s[4:5], 0, v12
	s_cmp_eq_u32 s73, 3
	s_nop 0
	v_cndmask_b32_e64 v22, 0, 1, s[4:5]
	s_waitcnt vmcnt(3)
	v_cmp_ne_u32_e64 s[4:5], 0, v14
	s_nop 1
	v_cndmask_b32_e64 v23, 0, 1, s[4:5]
	v_cmp_ne_u32_e64 s[4:5], 0, v1
	s_nop 1
	v_addc_co_u32_e64 v1, s[4:5], 0, v17, s[4:5]
	v_addc_co_u32_e32 v1, vcc, v1, v18, vcc
	s_cselect_b64 vcc, -1, 0
	s_cmp_eq_u32 s73, 4
	v_cndmask_b32_e32 v2, v2, v5, vcc
	s_cselect_b64 vcc, -1, 0
	s_cmp_eq_u32 s73, 5
	v_cndmask_b32_e32 v2, v2, v6, vcc
	s_cselect_b64 vcc, -1, 0
	s_cmp_eq_u32 s73, 6
	v_cndmask_b32_e32 v2, v2, v7, vcc
	s_cselect_b64 vcc, -1, 0
	s_cmp_eq_u32 s73, 7
	v_cmp_ne_u32_e64 s[4:5], 0, v7
	v_cndmask_b32_e32 v2, v2, v8, vcc
	s_cselect_b64 vcc, -1, 0
	s_cmp_eq_u32 s73, 8
	v_addc_co_u32_e64 v1, s[4:5], v1, v19, s[4:5]
	v_cndmask_b32_e32 v2, v2, v9, vcc
	s_cselect_b64 vcc, -1, 0
	s_cmp_eq_u32 s73, 9
	v_cmp_ne_u32_e64 s[4:5], 0, v9
	v_cndmask_b32_e32 v2, v2, v10, vcc
	s_cselect_b64 vcc, -1, 0
	s_cmp_eq_u32 s73, 10
	v_addc_co_u32_e64 v1, s[4:5], v1, v20, s[4:5]
	v_cndmask_b32_e32 v2, v2, v11, vcc
	s_cselect_b64 vcc, -1, 0
	s_cmp_eq_u32 s73, 11
	v_cmp_ne_u32_e64 s[4:5], 0, v11
	v_cndmask_b32_e32 v2, v2, v12, vcc
	s_cselect_b64 vcc, -1, 0
	s_cmp_eq_u32 s73, 12
	v_addc_co_u32_e64 v1, s[4:5], v1, v21, s[4:5]
	v_cndmask_b32_e32 v2, v2, v13, vcc
	s_cselect_b64 vcc, -1, 0
	s_cmp_eq_u32 s73, 13
	v_cmp_ne_u32_e64 s[4:5], 0, v13
	v_cndmask_b32_e32 v2, v2, v14, vcc
	s_cselect_b64 vcc, -1, 0
	v_addc_co_u32_e64 v1, s[4:5], v1, v22, s[4:5]
	s_waitcnt vmcnt(2)
	v_cndmask_b32_e32 v2, v2, v15, vcc
	s_waitcnt vmcnt(1)
	v_cmp_ne_u32_e32 vcc, 0, v16
	s_cmp_eq_u32 s73, 14
	v_cmp_ne_u32_e64 s[4:5], 0, v15
	v_cndmask_b32_e64 v3, 0, 1, vcc
	s_cselect_b64 vcc, -1, 0
	v_addc_co_u32_e64 v1, s[4:5], v1, v23, s[4:5]
	v_cndmask_b32_e32 v2, v2, v16, vcc
	s_waitcnt vmcnt(0)
	v_cmp_ne_u32_e32 vcc, 0, v0
	s_cmp_eq_u32 s73, 15
	v_mov_b32_e32 v10, v254
	v_addc_co_u32_e32 v1, vcc, v1, v3, vcc
	s_cselect_b64 vcc, -1, 0
	s_add_u32 s12, s36, 0x2e00000
	s_addc_u32 s13, s37, 0
	s_add_u32 s30, s36, 0x200000
	v_cndmask_b32_e32 v0, v2, v0, vcc
	s_addc_u32 s31, s37, 0
	v_max_u32_e32 v0, 1, v0
	s_add_u32 s8, s36, 0xa00000
	v_readfirstlane_b32 s0, v0
	v_max_u32_e32 v0, 1, v1
	s_addc_u32 s9, s37, 0
	v_writelane_b32 v255, s0, 1
	v_readfirstlane_b32 s0, v0
	s_cmpk_lt_i32 s33, 0xa00
	s_nop 0
	v_writelane_b32 v255, s0, 2
	s_cselect_b64 s[0:1], -1, 0
	v_writelane_b32 v255, s0, 3
	v_readfirstlane_b32 s5, v10
	s_and_b64 vcc, exec, s[0:1]
	v_writelane_b32 v255, s1, 4
	s_cbranch_vccz .LBB0_235
; #define PG8_STAGE(bufoff, gbase, voff) do { _Pragma("unroll") for (int _i = 0; _i < 2; ++_i) \
;         __builtin_amdgcn_global_load_lds((const unsigned*)((const char*)(gbase) + (voff)[_i]), (LAS unsigned*)(lds + (bufoff) + ldsw + _i * 8192), 16, 0, 0); } while (0)
; #define PG8_WAIT_V(n) asm volatile("s_waitcnt vmcnt(" #n ")" ::: "memory")
; #define PG8_BAR __builtin_amdgcn_s_barrier()
; template <class Epi, class Sched>
; __device__ __forceinline__ void gemm_phase(LAS unsigned char* lds, const int K, const int lda, const int ldb, const Sched& S, const Epi& E) {
;     ...
;     const int wid = __builtin_amdgcn_readfirstlane(tid >> 6), lane = tid & 63, wr = wid >> 2, wc = wid & 3, fr = lane & 15, fq = lane >> 4;
;     const int nt = K / BK;
;     unsigned voffA[2], voffB[2];
; #pragma unroll
;     for (int i = 0; i < 2; ++i) { int R, C; stage_rc(tid * 16 + i * 8192, R, C); const int Rb = (R & ~31) + perm32(R & 31);
;         voffA[i] = (unsigned)(R * lda + C) * 2u; voffB[i] = (unsigned)(Rb * ldb + C) * 2u; }
;     const size_t kstep = (size_t)(BK * 2);
;     const size_t hA = (size_t)HALF * lda * 2, hB = (size_t)HALF * ldb * 2;
;     const unsigned ldsw = (unsigned)wid * 1024u;
;     const int aoff = lds_byte(wr * 64 + fr, fq * 8), boff = lds_byte(wc * 32 + fr, fq * 8);
;     ...
;     Unit cur, nxt; int ui = 0;
;     if (!S.next(0, cur)) return;
;     f32x4 acc[2][2][4][2];
; #pragma unroll
;     for (int a = 0; a < 2; ++a)
; #pragma unroll
;         for (int b = 0; b < 2; ++b)
; #pragma unroll
;             for (int m = 0; m < 4; ++m)
; #pragma unroll
;                 for (int n = 0; n < 2; ++n) acc[a][b][m][n] = (f32x4){0.f, 0.f, 0.f, 0.f};
;     bf16x8 At[4][2], B0[2][2], B1[2][2];
;     const char* cA = S.aptr(cur); const char* cB = S.bptr(cur);
;     PG8_STAGE(PG8_SB(0, 0), cB, voffB); PG8_STAGE(PG8_SB(0, 1), cB + hB, voffB); PG8_STAGE(PG8_SA(0, 0), cA, voffA); PG8_STAGE(PG8_SA(0, 1), cA + hA, voffA);
;     if (wr == 1) PG8_BAR;
;     PG8_WAIT_V(2); PG8_BAR;
;     PG8_STAGE(PG8_SB(1, 0), cB + kstep, voffB); PG8_STAGE(PG8_SA(1, 0), cA + kstep, voffA); PG8_STAGE(PG8_SB(1, 1), cB + hB + kstep, voffB);
;     PG8_WAIT_V(6); PG8_BAR;
	v_lshlrev_b32_e32 v0, 4, v10
	v_add_u32_e32 v1, 0x2000, v0
	v_ashrrev_i32_e32 v2, 31, v1
	v_lshrrev_b32_e32 v2, 22, v2
	v_add_u32_e32 v2, v1, v2
	v_ashrrev_i32_e32 v8, 10, v2
	v_mul_i32_i24_e32 v2, 0x400, v8
	v_sub_u32_e32 v1, v1, v2
	v_lshrrev_b32_e32 v2, 4, v1
	v_bitop3_b32 v1, v2, v1, 32 bitop3:0x6c
	v_ashrrev_i32_e32 v2, 31, v1
	v_lshrrev_b32_e32 v2, 26, v2
	v_add_u32_e32 v2, v1, v2
	v_lshlrev_b32_e32 v3, 3, v8
	v_ashrrev_i32_e32 v9, 6, v2
	v_and_b32_e32 v3, -16, v3
	v_add_u32_e32 v3, v9, v3
	v_and_b32_e32 v4, 3, v9
	s_mov_b32 s0, 0xfffe0
	v_lshrrev_b32_e32 v5, 2, v3
	v_lshlrev_b32_e32 v6, 1, v3
	v_and_b32_e32 v2, 0xc0, v2
	v_and_or_b32 v4, v3, s0, v4
	v_and_b32_e32 v5, 4, v5
	v_and_b32_e32 v6, 24, v6
	v_sub_u32_e32 v1, v1, v2
	v_mov_b32_e32 v2, 1
	v_or3_b32 v4, v4, v5, v6
	v_lshlrev_b32_e32 v5, 5, v8
	v_ashrrev_i16_sdwa v1, v2, sext(v1) dst_sel:DWORD dst_unused:UNUSED_PAD src0_sel:DWORD src1_sel:BYTE_0
	v_and_b32_e32 v5, 32, v5
	v_bfe_i32 v11, v1, 0, 16
	v_add_lshl_u32 v1, v5, v11, 1
	v_and_b32_e32 v242, 63, v254
	v_lshrrev_b32_e32 v243, 6, v254
	v_lshrrev_b32_e32 v244, 3, v242
	v_lshl_add_u32 v245, v243, 3, v244
	v_and_b32_e32 v246, 1, v243
	v_bfe_u32 v247, v242, 4, 2
	v_lshl_add_u32 v247, v246, 2, v247
	v_and_b32_e32 v237, 7, v242
	v_xor_b32_e32 v247, v237, v247
	v_lshlrev_b32_e32 v247, 4, v247
	v_lshl_add_u32 v236, v245, 12, v247
	v_add_u32_e32 v237, 0x40000, v236
	v_lshrrev_b32_e32 v245, 5, v242
	v_lshlrev_b32_e32 v245, 3, v245
	v_lshl_add_u32 v245, v246, 4, v245
	v_bfe_u32 v246, v243, 1, 1
	v_lshl_add_u32 v245, v246, 2, v245
	v_and_b32_e32 v246, 3, v244
	v_add_u32_e32 v245, v245, v246
	v_lshrrev_b32_e32 v246, 2, v243
	v_lshl_add_u32 v245, v246, 5, v245
	v_lshl_add_u32 v238, v245, 12, v247
	v_add_u32_e32 v239, 0x40000, v238
	v_and_b32_e32 v242, 15, v254
	v_bfe_u32 v244, v254, 4, 2
	v_bfe_u32 v245, v254, 1, 3
	v_xor_b32_e32 v244, v244, v245
	v_lshlrev_b32_e32 v244, 4, v244
	v_lshl_add_u32 v244, v242, 7, v244
	v_lshrrev_b32_e32 v245, 8, v254
	v_lshl_add_u32 v240, v245, 13, v244
	v_and_b32_e32 v245, 3, v243
	v_lshl_add_u32 v241, v245, 13, v244
	v_and_b32_e32 v242, 63, v254
	v_lshrrev_b32_e32 v243, 6, v254
	v_lshrrev_b32_e32 v244, 3, v242
	v_and_b32_e32 v246, 1, v243
	v_bfe_u32 v247, v242, 4, 2
	v_lshl_add_u32 v247, v246, 2, v247
	v_and_b32_e32 v245, 7, v242
	v_xor_b32_e32 v247, v245, v247
	v_lshlrev_b32_e32 v247, 4, v247
	v_lshlrev_b32_e32 v245, 5, v246
	v_lshl_add_u32 v245, v244, 2, v245
	v_bfe_u32 v246, v243, 1, 2
	v_add_u32_e32 v245, v245, v246
	v_lshl_add_u32 v238, v245, 12, v247
	v_add_u32_e32 v239, 0x40000, v238
	v_mov_b32_e32 v128, v239
	v_mov_b32_e32 v130, v237
	v_bfe_i32 v1, v10, 27, 1
	v_lshrrev_b32_e32 v1, 22, v1
	v_add_u32_e32 v1, v0, v1
	v_and_b32_e32 v1, 0xfffffc00, v1
	v_sub_u32_e32 v0, v0, v1
	v_lshrrev_b32_e32 v1, 4, v0
	v_ashrrev_i32_e32 v3, 31, v10
	v_bitop3_b32 v0, v1, v0, 32 bitop3:0x6c
	v_lshrrev_b32_e32 v3, 26, v3
	v_ashrrev_i32_e32 v1, 31, v0
	v_add_u32_e32 v3, v10, v3
	v_lshrrev_b32_e32 v1, 26, v1
	v_ashrrev_i32_e32 v13, 6, v3
	v_add_u32_e32 v1, v0, v1
	v_lshlrev_b32_e32 v3, 3, v13
	v_ashrrev_i32_e32 v12, 6, v1
	v_and_b32_e32 v3, -16, v3
	v_add_u32_e32 v3, v12, v3
	v_and_b32_e32 v4, 3, v12
	s_ashr_i32 s14, s33, 31
	v_and_or_b32 v4, v3, s0, v4
	s_lshr_b32 s0, s14, 29
	s_add_i32 s0, s33, s0
	s_ashr_i32 s18, s5, 6
	s_ashr_i32 s1, s0, 3
	s_and_b32 s0, s0, -8
	s_ashr_i32 s19, s5, 8
	s_lshl_b32 s2, s18, 10
	s_sub_i32 s0, s33, s0
	s_cmp_lt_i32 s0, 0
	s_movk_i32 s15, 0x141
	s_cselect_b32 s4, s15, 0x140
	s_mul_i32 s0, s4, s0
	s_add_i32 s0, s0, s1
	s_mul_hi_i32 s1, s0, 0x66666667
	s_lshr_b32 s4, s1, 31
	s_ashr_i32 s1, s1, 6
	s_add_i32 s1, s1, s4
	s_lshl_b32 s6, s1, 3
	s_mulk_i32 s1, 0xa0
	s_sub_i32 s0, s0, s1
	s_sext_i32_i16 s1, s0
	s_bfe_u32 s1, s1, 0x3001c
	s_add_i32 s1, s0, s1
	s_sext_i32_i16 s4, s1
	s_and_b32 s1, s1, 0xfff8
	s_sub_i32 s0, s0, s1
	s_sext_i32_i16 s0, s0
	v_lshrrev_b32_e32 v5, 2, v3
	v_lshlrev_b32_e32 v6, 1, v3
	v_and_b32_e32 v1, 0xc0, v1
	s_lshr_b32 s4, s4, 3
	s_add_i32 s6, s6, s0
	v_and_b32_e32 v5, 4, v5
	v_and_b32_e32 v6, 24, v6
	v_sub_u32_e32 v0, v0, v1
	s_ashr_i32 s7, s6, 31
	s_bfe_i64 s[0:1], s[4:5], 0x100000
	v_or3_b32 v4, v4, v5, v6
	v_lshlrev_b32_e32 v5, 5, v13
	v_ashrrev_i16_sdwa v0, v2, sext(v0) dst_sel:DWORD dst_unused:UNUSED_PAD src0_sel:DWORD src1_sel:BYTE_0
	s_lshl_b64 s[10:11], s[6:7], 20
	s_lshl_b64 s[0:1], s[0:1], 20
	v_and_b32_e32 v5, 32, v5
	v_bfe_i32 v14, v0, 0, 16
	s_add_u32 s54, s8, s0
	v_add_lshl_u32 v0, v5, v14, 1
	s_addc_u32 s55, s9, s1
	s_add_i32 s1, s2, 0
	v_mov_b32_e32 v132, v238
	s_add_i32 m0, s1, 0x10000
	v_mov_b32_e32 v134, v236
	global_load_lds_dwordx4 v132, s[54:55]
	s_add_i32 m0, s1, 0x12000
	s_add_u32 s20, s54, 0x80000
	global_load_lds_dwordx4 v128, s[54:55]
	s_addc_u32 s21, s55, 0
	s_add_i32 m0, s1, 0x14000
	v_mov_b32_e32 v137, 0
	global_load_lds_dwordx4 v132, s[20:21]
	s_add_i32 m0, s1, 0x16000
	s_add_u32 s56, s12, s10
	s_addc_u32 s57, s13, s11
	s_add_i32 s17, s1, 0x2000
	global_load_lds_dwordx4 v128, s[20:21]
	s_mov_b32 m0, s1
	s_add_u32 s10, s56, 0x80000
	global_load_lds_dwordx4 v134, s[56:57]
	s_mov_b32 m0, s17
	s_addc_u32 s11, s57, 0
	s_add_i32 s29, s1, 0x4000
	global_load_lds_dwordx4 v130, s[56:57]
	s_mov_b32 m0, s29
	s_add_i32 s34, s1, 0x6000
	global_load_lds_dwordx4 v134, s[10:11]
	s_mov_b32 m0, s34
	v_mov_b32_e32 v133, v137
	global_load_lds_dwordx4 v130, s[10:11]
	v_mov_b32_e32 v129, v137
	v_mov_b32_e32 v135, v137
	v_mov_b32_e32 v131, v137
	s_cmp_eq_u32 s19, 1
	v_lshl_add_u64 v[6:7], s[54:55], 0, v[132:133]
	v_lshl_add_u64 v[4:5], s[54:55], 0, v[128:129]
	v_lshl_add_u64 v[0:1], s[56:57], 0, v[134:135]
	s_cselect_b64 s[10:11], -1, 0
	s_cmp_lg_u32 s19, 1
	v_lshl_add_u64 v[2:3], s[56:57], 0, v[130:131]
	s_cbranch_scc1 .LBB0_203
	s_barrier

; #define PG8_STAGE(bufoff, gbase, voff) do { _Pragma("unroll") for (int _i = 0; _i < 2; ++_i) \
;         __builtin_amdgcn_global_load_lds((const unsigned*)((const char*)(gbase) + (voff)[_i]), (LAS unsigned*)(lds + (bufoff) + ldsw + _i * 8192), 16, 0, 0); } while (0)
; #define PG8_LDA(dst, b, h) do { _Pragma("unroll") for (int m = 0; m < 4; ++m) _Pragma("unroll") for (int k = 0; k < 2; ++k) dst[m][k] = *(const LAS bf16x8*)(lds + PG8_SA(b, h) + aoff + m * 2048 + k * 1024); } while (0)
; #define PG8_LDB(dst, b, h) do { _Pragma("unroll") for (int n = 0; n < 2; ++n) _Pragma("unroll") for (int k = 0; k < 2; ++k) dst[n][k] = *(const LAS bf16x8*)(lds + PG8_SB(b, h) + boff + n * 2048 + k * 1024); } while (0)
; #define PG8_MMA(ai, bj, At, Bt) do { __builtin_amdgcn_s_setprio(1); _Pragma("unroll") for (int m = 0; m < 4; ++m) _Pragma("unroll") for (int n = 0; n < 2; ++n) _Pragma("unroll") for (int k = 0; k < 2; ++k) \
;         acc[ai][bj][m][n] = __builtin_amdgcn_mfma_f32_16x16x32_bf16(Bt[n][k], At[m][k], acc[ai][bj][m][n], 0, 0, 0); __builtin_amdgcn_s_setprio(0); } while (0)
; #define PG8_WAIT_V(n) asm volatile("s_waitcnt vmcnt(" #n ")" ::: "memory")
; #define PG8_WAIT_L(n) asm volatile("s_waitcnt lgkmcnt(" #n ")" ::: "memory")
; #define PG8_BAR __builtin_amdgcn_s_barrier()
; #define PG8_SCHED __builtin_amdgcn_sched_barrier(0)
; template <class Epi, class Sched>
; __device__ __forceinline__ void gemm_phase(LAS unsigned char* lds, const int K, const int lda, const int ldb, const Sched& S, const Epi& E) {
;     ...
;             PG8_LDB(B0, 0, 0); PG8_LDB(B1, 0, 1); PG8_SCHED; PG8_LDA(At, 0, 0); PG8_STAGE(PG8_SA(1, 1), a1 + hA, voffA);
;             PG8_WAIT_V(8); PG8_WAIT_L(0); PG8_BAR; PG8_MMA(0, 0, At, B0); PG8_MMA(0, 1, At, B1); PG8_BAR; PG8_SCHED;
;             PG8_LDA(At, 0, 1); PG8_STAGE(PG8_SB(0, 0), b2, voffB); PG8_STAGE(PG8_SB(0, 1), b2 + hB, voffB); PG8_STAGE(PG8_SA(0, 0), a2, voffA);
;             PG8_WAIT_V(8); PG8_WAIT_L(0); PG8_BAR; PG8_MMA(1, 0, At, B0); PG8_MMA(1, 1, At, B1); PG8_BAR; PG8_SCHED;
.LBB0_209:
	ds_read_b128 v[174:177], v188
	ds_read_b128 v[178:181], v147
	ds_read_b128 v[190:193], v188 offset:2048
	ds_read_b128 v[194:197], v147 offset:2048
	ds_read_b128 v[198:201], v189
	ds_read_b128 v[202:205], v149
	ds_read_b128 v[206:209], v189 offset:2048
	ds_read_b128 v[210:213], v149 offset:2048
	s_add_u32 s49, s54, 0xfff80080
	s_addc_u32 s56, s55, -1
	s_cmp_eq_u32 s47, 28
	s_cselect_b32 s59, s7, s56
	s_cselect_b32 s58, s18, s49
	s_cselect_b32 s57, s19, s45
	s_cselect_b32 s56, s20, s43
	v_lshl_add_u64 v[182:183], s[54:55], 0, v[140:141]
	s_add_i32 m0, s1, 0xc000
	ds_read_b128 v[214:217], v163
	ds_read_b128 v[218:221], v145
	ds_read_b128 v[222:225], v163 offset:2048
	ds_read_b128 v[226:229], v145 offset:2048
	ds_read_b128 v[230:233], v163 offset:4096
	ds_read_b128 v[236:239], v145 offset:4096
	ds_read_b128 v[240:243], v163 offset:6144
	ds_read_b128 v[244:247], v145 offset:6144
	global_load_lds_dwordx4 v[182:183], off
	v_lshl_add_u64 v[182:183], s[54:55], 0, v[138:139]
	s_add_i32 m0, s1, 0xe000
	s_nop 0
	global_load_lds_dwordx4 v[182:183], off
	s_waitcnt vmcnt(8)
	s_waitcnt lgkmcnt(0)
	s_barrier
	s_setprio 1
	s_waitcnt lgkmcnt(0)
	v_mfma_f32_16x16x32_bf16 v[124:127], v[214:217], v[174:177], v[124:127]
	v_mfma_f32_16x16x32_bf16 v[120:123], v[214:217], v[190:193], v[120:123]
	v_mfma_f32_16x16x32_bf16 v[108:111], v[222:225], v[174:177], v[108:111]
	v_mfma_f32_16x16x32_bf16 v[104:107], v[222:225], v[190:193], v[104:107]
	v_mfma_f32_16x16x32_bf16 v[92:95], v[230:233], v[174:177], v[92:95]
	v_mfma_f32_16x16x32_bf16 v[88:91], v[230:233], v[190:193], v[88:91]
	v_mfma_f32_16x16x32_bf16 v[76:79], v[240:243], v[174:177], v[76:79]
	v_mfma_f32_16x16x32_bf16 v[72:75], v[240:243], v[190:193], v[72:75]
	v_mfma_f32_16x16x32_bf16 v[124:127], v[218:221], v[178:181], v[124:127]
	v_mfma_f32_16x16x32_bf16 v[120:123], v[218:221], v[194:197], v[120:123]
	v_mfma_f32_16x16x32_bf16 v[108:111], v[226:229], v[178:181], v[108:111]
	v_mfma_f32_16x16x32_bf16 v[104:107], v[226:229], v[194:197], v[104:107]
	v_mfma_f32_16x16x32_bf16 v[92:95], v[236:239], v[178:181], v[92:95]
	v_mfma_f32_16x16x32_bf16 v[88:91], v[236:239], v[194:197], v[88:91]
	v_mfma_f32_16x16x32_bf16 v[76:79], v[244:247], v[178:181], v[76:79]
	v_mfma_f32_16x16x32_bf16 v[72:75], v[244:247], v[194:197], v[72:75]
	s_setprio 0
	s_setprio 1
	v_mfma_f32_16x16x32_bf16 v[116:119], v[214:217], v[198:201], v[116:119]
	v_mfma_f32_16x16x32_bf16 v[112:115], v[214:217], v[206:209], v[112:115]
	v_mfma_f32_16x16x32_bf16 v[100:103], v[222:225], v[198:201], v[100:103]
	v_mfma_f32_16x16x32_bf16 v[96:99], v[222:225], v[206:209], v[96:99]
	v_mfma_f32_16x16x32_bf16 v[84:87], v[230:233], v[198:201], v[84:87]
	v_mfma_f32_16x16x32_bf16 v[80:83], v[230:233], v[206:209], v[80:83]
	v_mfma_f32_16x16x32_bf16 v[68:71], v[240:243], v[198:201], v[68:71]
	v_mfma_f32_16x16x32_bf16 v[64:67], v[240:243], v[206:209], v[64:67]
	v_mfma_f32_16x16x32_bf16 v[116:119], v[218:221], v[202:205], v[116:119]
	v_mfma_f32_16x16x32_bf16 v[112:115], v[218:221], v[210:213], v[112:115]
	v_mfma_f32_16x16x32_bf16 v[100:103], v[226:229], v[202:205], v[100:103]
	v_mfma_f32_16x16x32_bf16 v[96:99], v[226:229], v[210:213], v[96:99]
	v_mfma_f32_16x16x32_bf16 v[84:87], v[236:239], v[202:205], v[84:87]
	v_mfma_f32_16x16x32_bf16 v[80:83], v[236:239], v[210:213], v[80:83]
	v_mfma_f32_16x16x32_bf16 v[68:71], v[244:247], v[202:205], v[68:71]
	v_mfma_f32_16x16x32_bf16 v[64:67], v[244:247], v[210:213], v[64:67]
	s_setprio 0
	s_barrier
	s_add_i32 s49, s68, s2
	v_lshl_add_u64 v[182:183], s[56:57], 0, v[132:133]
	s_mov_b32 m0, s49
	ds_read_b128 v[214:217], v163 offset:16384
	ds_read_b128 v[218:221], v145 offset:16384
	ds_read_b128 v[222:225], v163 offset:18432
	ds_read_b128 v[226:229], v145 offset:18432
	ds_read_b128 v[230:233], v163 offset:20480
	ds_read_b128 v[236:239], v145 offset:20480
	ds_read_b128 v[240:243], v163 offset:22528
	ds_read_b128 v[244:247], v145 offset:22528
	global_load_lds_dwordx4 v[182:183], off
	s_add_i32 m0, s49, 0x2000
	s_add_u32 s60, s56, 0x80000
	v_lshl_add_u64 v[248:249], s[56:57], 0, v[128:129]
	s_addc_u32 s61, s57, 0
	s_add_i32 s49, s69, s2
	global_load_lds_dwordx4 v[248:249], off
	v_lshl_add_u64 v[250:251], s[60:61], 0, v[132:133]
	s_mov_b32 m0, s49
	v_lshl_add_u64 v[252:253], s[58:59], 0, v[130:131]
	global_load_lds_dwordx4 v[250:251], off
	v_lshl_add_u64 v[250:251], s[60:61], 0, v[128:129]
	s_add_i32 m0, s49, 0x2000
	s_nop 0
	global_load_lds_dwordx4 v[250:251], off
	v_lshl_add_u64 v[250:251], s[58:59], 0, v[134:135]
	s_mov_b32 m0, s1
	s_nop 0
	global_load_lds_dwordx4 v[250:251], off
	s_mov_b32 m0, s17
	s_nop 0
	global_load_lds_dwordx4 v[252:253], off
	s_waitcnt vmcnt(8)
	s_waitcnt lgkmcnt(0)
	s_barrier
; #define PG8_STAGE(bufoff, gbase, voff) do { _Pragma("unroll") for (int _i = 0; _i < 2; ++_i) \
;         __builtin_amdgcn_global_load_lds((const unsigned*)((const char*)(gbase) + (voff)[_i]), (LAS unsigned*)(lds + (bufoff) + ldsw + _i * 8192), 16, 0, 0); } while (0)
; #define PG8_LDA(dst, b, h) do { _Pragma("unroll") for (int m = 0; m < 4; ++m) _Pragma("unroll") for (int k = 0; k < 2; ++k) dst[m][k] = *(const LAS bf16x8*)(lds + PG8_SA(b, h) + aoff + m * 2048 + k * 1024); } while (0)
; #define PG8_LDB(dst, b, h) do { _Pragma("unroll") for (int n = 0; n < 2; ++n) _Pragma("unroll") for (int k = 0; k < 2; ++k) dst[n][k] = *(const LAS bf16x8*)(lds + PG8_SB(b, h) + boff + n * 2048 + k * 1024); } while (0)
; #define PG8_MMA(ai, bj, At, Bt) do { __builtin_amdgcn_s_setprio(1); _Pragma("unroll") for (int m = 0; m < 4; ++m) _Pragma("unroll") for (int n = 0; n < 2; ++n) _Pragma("unroll") for (int k = 0; k < 2; ++k) \
;         acc[ai][bj][m][n] = __builtin_amdgcn_mfma_f32_16x16x32_bf16(Bt[n][k], At[m][k], acc[ai][bj][m][n], 0, 0, 0); __builtin_amdgcn_s_setprio(0); } while (0)
; #define PG8_WAIT_V(n) asm volatile("s_waitcnt vmcnt(" #n ")" ::: "memory")
; #define PG8_WAIT_L(n) asm volatile("s_waitcnt lgkmcnt(" #n ")" ::: "memory")
; #define PG8_BAR __builtin_amdgcn_s_barrier()
; #define PG8_SCHED __builtin_amdgcn_sched_barrier(0)
; template <class Epi, class Sched>
; __device__ __forceinline__ void gemm_phase(LAS unsigned char* lds, const int K, const int lda, const int ldb, const Sched& S, const Epi& E) {
;     ...
;             PG8_WAIT_V(8); PG8_WAIT_L(0); PG8_BAR; PG8_MMA(1, 0, At, B0); PG8_MMA(1, 1, At, B1); PG8_BAR; PG8_SCHED;
;             PG8_LDB(B0, 1, 0); PG8_LDB(B1, 1, 1); PG8_SCHED; PG8_LDA(At, 1, 0); PG8_STAGE(PG8_SA(0, 1), a2 + hA, voffA);
;             PG8_WAIT_V(8); PG8_WAIT_L(0); PG8_BAR; PG8_MMA(0, 0, At, B0); PG8_MMA(0, 1, At, B1); PG8_BAR; PG8_SCHED;
;             PG8_LDA(At, 1, 1); PG8_STAGE(PG8_SB(1, 0), b3, voffB); PG8_STAGE(PG8_SB(1, 1), b3 + hB, voffB); PG8_STAGE(PG8_SA(1, 0), a3, voffA);
;             PG8_WAIT_V(8); PG8_WAIT_L(0); PG8_BAR; PG8_MMA(1, 0, At, B0); PG8_MMA(1, 1, At, B1); PG8_BAR; PG8_SCHED;
	s_setprio 1
	s_waitcnt lgkmcnt(0)
	v_mfma_f32_16x16x32_bf16 v[60:63], v[214:217], v[174:177], v[60:63]
	v_mfma_f32_16x16x32_bf16 v[56:59], v[214:217], v[190:193], v[56:59]
	v_mfma_f32_16x16x32_bf16 v[44:47], v[222:225], v[174:177], v[44:47]
	v_mfma_f32_16x16x32_bf16 v[40:43], v[222:225], v[190:193], v[40:43]
	v_mfma_f32_16x16x32_bf16 v[28:31], v[230:233], v[174:177], v[28:31]
	v_mfma_f32_16x16x32_bf16 v[24:27], v[230:233], v[190:193], v[24:27]
	v_mfma_f32_16x16x32_bf16 v[12:15], v[240:243], v[174:177], v[12:15]
	v_mfma_f32_16x16x32_bf16 v[8:11], v[240:243], v[190:193], v[8:11]
	v_mfma_f32_16x16x32_bf16 v[60:63], v[218:221], v[178:181], v[60:63]
	v_mfma_f32_16x16x32_bf16 v[56:59], v[218:221], v[194:197], v[56:59]
	v_mfma_f32_16x16x32_bf16 v[44:47], v[226:229], v[178:181], v[44:47]
	v_mfma_f32_16x16x32_bf16 v[40:43], v[226:229], v[194:197], v[40:43]
	v_mfma_f32_16x16x32_bf16 v[28:31], v[236:239], v[178:181], v[28:31]
	v_mfma_f32_16x16x32_bf16 v[24:27], v[236:239], v[194:197], v[24:27]
	v_mfma_f32_16x16x32_bf16 v[12:15], v[244:247], v[178:181], v[12:15]
	v_mfma_f32_16x16x32_bf16 v[8:11], v[244:247], v[194:197], v[8:11]
	s_setprio 0
	s_setprio 1
	v_mfma_f32_16x16x32_bf16 v[52:55], v[214:217], v[198:201], v[52:55]
	v_mfma_f32_16x16x32_bf16 v[48:51], v[214:217], v[206:209], v[48:51]
	v_mfma_f32_16x16x32_bf16 v[36:39], v[222:225], v[198:201], v[36:39]
	v_mfma_f32_16x16x32_bf16 v[32:35], v[222:225], v[206:209], v[32:35]
	v_mfma_f32_16x16x32_bf16 v[20:23], v[230:233], v[198:201], v[20:23]
	v_mfma_f32_16x16x32_bf16 v[16:19], v[230:233], v[206:209], v[16:19]
	v_mfma_f32_16x16x32_bf16 v[4:7], v[240:243], v[198:201], v[4:7]
	v_mfma_f32_16x16x32_bf16 v[0:3], v[240:243], v[206:209], v[0:3]
	v_mfma_f32_16x16x32_bf16 v[52:55], v[218:221], v[202:205], v[52:55]
	v_mfma_f32_16x16x32_bf16 v[48:51], v[218:221], v[210:213], v[48:51]
	v_mfma_f32_16x16x32_bf16 v[36:39], v[226:229], v[202:205], v[36:39]
	v_mfma_f32_16x16x32_bf16 v[32:35], v[226:229], v[210:213], v[32:35]
	v_mfma_f32_16x16x32_bf16 v[20:23], v[236:239], v[202:205], v[20:23]
	v_mfma_f32_16x16x32_bf16 v[16:19], v[236:239], v[210:213], v[16:19]
	v_mfma_f32_16x16x32_bf16 v[4:7], v[244:247], v[202:205], v[4:7]
	v_mfma_f32_16x16x32_bf16 v[0:3], v[244:247], v[210:213], v[0:3]
	s_setprio 0
	s_barrier
	s_add_i32 s49, 0, 0x18000
	v_add_u32_e32 v143, s49, v161
	v_add_u32_e32 v158, s49, v151
	s_add_i32 s60, 0, 0x1c000
	ds_read_b128 v[174:177], v143
	ds_read_b128 v[178:181], v158
	ds_read_b128 v[190:193], v143 offset:2048
	ds_read_b128 v[194:197], v158 offset:2048
	v_add_u32_e32 v143, 0x19000, v161
	v_add_u32_e32 v158, 0x19000, v151
	ds_read_b128 v[198:201], v143
	ds_read_b128 v[202:205], v158
	ds_read_b128 v[206:209], v143 offset:2048
	ds_read_b128 v[210:213], v158 offset:2048
	s_add_u32 s58, s58, 0x80000
	s_addc_u32 s59, s59, 0
	s_mov_b32 m0, s29
	v_lshl_add_u64 v[234:235], s[58:59], 0, v[134:135]
	ds_read_b128 v[214:217], v163 offset:32768
	ds_read_b128 v[218:221], v145 offset:32768
	ds_read_b128 v[222:225], v163 offset:34816
	ds_read_b128 v[226:229], v145 offset:34816
	ds_read_b128 v[230:233], v163 offset:36864
	ds_read_b128 v[236:239], v145 offset:36864
	ds_read_b128 v[240:243], v163 offset:38912
	ds_read_b128 v[244:247], v145 offset:38912
	global_load_lds_dwordx4 v[234:235], off
	v_lshl_add_u64 v[234:235], s[58:59], 0, v[130:131]
	s_mov_b32 m0, s34
	s_nop 0
	global_load_lds_dwordx4 v[234:235], off
	s_waitcnt vmcnt(8)
	s_waitcnt lgkmcnt(0)
	s_barrier
	s_setprio 1
	s_waitcnt lgkmcnt(0)
	v_mfma_f32_16x16x32_bf16 v[124:127], v[214:217], v[174:177], v[124:127]
	v_mfma_f32_16x16x32_bf16 v[120:123], v[214:217], v[190:193], v[120:123]
	v_mfma_f32_16x16x32_bf16 v[108:111], v[222:225], v[174:177], v[108:111]
	v_mfma_f32_16x16x32_bf16 v[104:107], v[222:225], v[190:193], v[104:107]
	v_mfma_f32_16x16x32_bf16 v[92:95], v[230:233], v[174:177], v[92:95]
	v_mfma_f32_16x16x32_bf16 v[88:91], v[230:233], v[190:193], v[88:91]
	v_mfma_f32_16x16x32_bf16 v[76:79], v[240:243], v[174:177], v[76:79]
	v_mfma_f32_16x16x32_bf16 v[72:75], v[240:243], v[190:193], v[72:75]
	v_mfma_f32_16x16x32_bf16 v[124:127], v[218:221], v[178:181], v[124:127]
	v_mfma_f32_16x16x32_bf16 v[120:123], v[218:221], v[194:197], v[120:123]
	v_mfma_f32_16x16x32_bf16 v[108:111], v[226:229], v[178:181], v[108:111]
	v_mfma_f32_16x16x32_bf16 v[104:107], v[226:229], v[194:197], v[104:107]
	v_mfma_f32_16x16x32_bf16 v[92:95], v[236:239], v[178:181], v[92:95]
	v_mfma_f32_16x16x32_bf16 v[88:91], v[236:239], v[194:197], v[88:91]
	v_mfma_f32_16x16x32_bf16 v[76:79], v[244:247], v[178:181], v[76:79]
	v_mfma_f32_16x16x32_bf16 v[72:75], v[244:247], v[194:197], v[72:75]
	s_setprio 0
	s_setprio 1
	v_mfma_f32_16x16x32_bf16 v[116:119], v[214:217], v[198:201], v[116:119]
	v_mfma_f32_16x16x32_bf16 v[112:115], v[214:217], v[206:209], v[112:115]
	v_mfma_f32_16x16x32_bf16 v[100:103], v[222:225], v[198:201], v[100:103]
	v_mfma_f32_16x16x32_bf16 v[96:99], v[222:225], v[206:209], v[96:99]
	v_mfma_f32_16x16x32_bf16 v[84:87], v[230:233], v[198:201], v[84:87]
	v_mfma_f32_16x16x32_bf16 v[80:83], v[230:233], v[206:209], v[80:83]
	v_mfma_f32_16x16x32_bf16 v[68:71], v[240:243], v[198:201], v[68:71]
	v_mfma_f32_16x16x32_bf16 v[64:67], v[240:243], v[206:209], v[64:67]
	v_mfma_f32_16x16x32_bf16 v[116:119], v[218:221], v[202:205], v[116:119]
	v_mfma_f32_16x16x32_bf16 v[112:115], v[218:221], v[210:213], v[112:115]
	v_mfma_f32_16x16x32_bf16 v[100:103], v[226:229], v[202:205], v[100:103]
	v_mfma_f32_16x16x32_bf16 v[96:99], v[226:229], v[210:213], v[96:99]
	v_mfma_f32_16x16x32_bf16 v[84:87], v[236:239], v[202:205], v[84:87]
	v_mfma_f32_16x16x32_bf16 v[80:83], v[236:239], v[210:213], v[80:83]
	v_mfma_f32_16x16x32_bf16 v[68:71], v[244:247], v[202:205], v[68:71]
	v_mfma_f32_16x16x32_bf16 v[64:67], v[244:247], v[210:213], v[64:67]
	s_setprio 0
	s_barrier
; #define PG8_STAGE(bufoff, gbase, voff) do { _Pragma("unroll") for (int _i = 0; _i < 2; ++_i) \
;         __builtin_amdgcn_global_load_lds((const unsigned*)((const char*)(gbase) + (voff)[_i]), (LAS unsigned*)(lds + (bufoff) + ldsw + _i * 8192), 16, 0, 0); } while (0)
; #define PG8_LDA(dst, b, h) do { _Pragma("unroll") for (int m = 0; m < 4; ++m) _Pragma("unroll") for (int k = 0; k < 2; ++k) dst[m][k] = *(const LAS bf16x8*)(lds + PG8_SA(b, h) + aoff + m * 2048 + k * 1024); } while (0)
; #define PG8_MMA(ai, bj, At, Bt) do { __builtin_amdgcn_s_setprio(1); _Pragma("unroll") for (int m = 0; m < 4; ++m) _Pragma("unroll") for (int n = 0; n < 2; ++n) _Pragma("unroll") for (int k = 0; k < 2; ++k) \
;         acc[ai][bj][m][n] = __builtin_amdgcn_mfma_f32_16x16x32_bf16(Bt[n][k], At[m][k], acc[ai][bj][m][n], 0, 0, 0); __builtin_amdgcn_s_setprio(0); } while (0)
; #define PG8_WAIT_V(n) asm volatile("s_waitcnt vmcnt(" #n ")" ::: "memory")
; #define PG8_WAIT_L(n) asm volatile("s_waitcnt lgkmcnt(" #n ")" ::: "memory")
; #define PG8_BAR __builtin_amdgcn_s_barrier()
; #define PG8_SCHED __builtin_amdgcn_sched_barrier(0)
; template <class Epi, class Sched>
; __device__ __forceinline__ void gemm_phase(LAS unsigned char* lds, const int K, const int lda, const int ldb, const Sched& S, const Epi& E) {
;     ...
;             PG8_WAIT_V(8); PG8_WAIT_L(0); PG8_BAR; PG8_MMA(0, 0, At, B0); PG8_MMA(0, 1, At, B1); PG8_BAR; PG8_SCHED;
;             PG8_LDA(At, 1, 1); PG8_STAGE(PG8_SB(1, 0), b3, voffB); PG8_STAGE(PG8_SB(1, 1), b3 + hB, voffB); PG8_STAGE(PG8_SA(1, 0), a3, voffA);
;             PG8_WAIT_V(8); PG8_WAIT_L(0); PG8_BAR; PG8_MMA(1, 0, At, B0); PG8_MMA(1, 1, At, B1); PG8_BAR; PG8_SCHED;
;         }
	s_add_i32 s49, s49, s2
	v_lshl_add_u64 v[182:183], v[182:183], 0, s[22:23]
	s_mov_b32 m0, s49
	ds_read_b128 v[214:217], v163 offset:49152
	ds_read_b128 v[218:221], v145 offset:49152
	ds_read_b128 v[222:225], v163 offset:51200
	ds_read_b128 v[226:229], v145 offset:51200
	ds_read_b128 v[230:233], v163 offset:53248
	ds_read_b128 v[236:239], v145 offset:53248
	ds_read_b128 v[240:243], v163 offset:55296
	ds_read_b128 v[244:247], v145 offset:55296
	global_load_lds_dwordx4 v[182:183], off
	s_add_i32 m0, s49, 0x2000
	s_add_u32 s56, s56, 0x80080
	v_lshl_add_u64 v[182:183], v[248:249], 0, s[22:23]
	s_addc_u32 s57, s57, 0
	s_add_i32 s49, s60, s2
	global_load_lds_dwordx4 v[182:183], off
	v_lshl_add_u64 v[182:183], s[56:57], 0, v[132:133]
	s_mov_b32 m0, s49
	s_nop 0
	global_load_lds_dwordx4 v[182:183], off
	v_lshl_add_u64 v[182:183], s[56:57], 0, v[128:129]
	s_add_i32 m0, s49, 0x2000
	s_nop 0
	global_load_lds_dwordx4 v[182:183], off
	v_lshl_add_u64 v[182:183], v[250:251], 0, s[22:23]
	s_mov_b32 m0, s38
	s_nop 0
	global_load_lds_dwordx4 v[182:183], off
	v_lshl_add_u64 v[182:183], v[252:253], 0, s[22:23]
	s_mov_b32 m0, s39
	s_nop 0
	global_load_lds_dwordx4 v[182:183], off
	s_waitcnt vmcnt(8)
	s_waitcnt lgkmcnt(0)
	s_barrier
	s_setprio 1
	s_waitcnt lgkmcnt(0)
	v_mfma_f32_16x16x32_bf16 v[60:63], v[214:217], v[174:177], v[60:63]
	v_mfma_f32_16x16x32_bf16 v[56:59], v[214:217], v[190:193], v[56:59]
	v_mfma_f32_16x16x32_bf16 v[44:47], v[222:225], v[174:177], v[44:47]
	v_mfma_f32_16x16x32_bf16 v[40:43], v[222:225], v[190:193], v[40:43]
	v_mfma_f32_16x16x32_bf16 v[28:31], v[230:233], v[174:177], v[28:31]
	v_mfma_f32_16x16x32_bf16 v[24:27], v[230:233], v[190:193], v[24:27]
	v_mfma_f32_16x16x32_bf16 v[12:15], v[240:243], v[174:177], v[12:15]
	v_mfma_f32_16x16x32_bf16 v[8:11], v[240:243], v[190:193], v[8:11]
	v_mfma_f32_16x16x32_bf16 v[60:63], v[218:221], v[178:181], v[60:63]
	v_mfma_f32_16x16x32_bf16 v[56:59], v[218:221], v[194:197], v[56:59]
	v_mfma_f32_16x16x32_bf16 v[44:47], v[226:229], v[178:181], v[44:47]
	v_mfma_f32_16x16x32_bf16 v[40:43], v[226:229], v[194:197], v[40:43]
	v_mfma_f32_16x16x32_bf16 v[28:31], v[236:239], v[178:181], v[28:31]
	v_mfma_f32_16x16x32_bf16 v[24:27], v[236:239], v[194:197], v[24:27]
	v_mfma_f32_16x16x32_bf16 v[12:15], v[244:247], v[178:181], v[12:15]
	v_mfma_f32_16x16x32_bf16 v[8:11], v[244:247], v[194:197], v[8:11]
	s_setprio 0
	s_setprio 1
	v_mfma_f32_16x16x32_bf16 v[52:55], v[214:217], v[198:201], v[52:55]
	v_mfma_f32_16x16x32_bf16 v[48:51], v[214:217], v[206:209], v[48:51]
	v_mfma_f32_16x16x32_bf16 v[36:39], v[222:225], v[198:201], v[36:39]
	v_mfma_f32_16x16x32_bf16 v[32:35], v[222:225], v[206:209], v[32:35]
	v_mfma_f32_16x16x32_bf16 v[20:23], v[230:233], v[198:201], v[20:23]
	v_mfma_f32_16x16x32_bf16 v[16:19], v[230:233], v[206:209], v[16:19]
	v_mfma_f32_16x16x32_bf16 v[4:7], v[240:243], v[198:201], v[4:7]
	v_mfma_f32_16x16x32_bf16 v[0:3], v[240:243], v[206:209], v[0:3]
	v_mfma_f32_16x16x32_bf16 v[52:55], v[218:221], v[202:205], v[52:55]
	v_mfma_f32_16x16x32_bf16 v[48:51], v[218:221], v[210:213], v[48:51]
	v_mfma_f32_16x16x32_bf16 v[36:39], v[226:229], v[202:205], v[36:39]
	v_mfma_f32_16x16x32_bf16 v[32:35], v[226:229], v[210:213], v[32:35]
	v_mfma_f32_16x16x32_bf16 v[20:23], v[236:239], v[202:205], v[20:23]
	v_mfma_f32_16x16x32_bf16 v[16:19], v[236:239], v[210:213], v[16:19]
	v_mfma_f32_16x16x32_bf16 v[4:7], v[244:247], v[202:205], v[4:7]
	v_mfma_f32_16x16x32_bf16 v[0:3], v[244:247], v[210:213], v[0:3]
	s_setprio 0
	s_barrier
	s_add_i32 s47, s47, 2
	s_add_u32 s43, s43, 0x100
	s_addc_u32 s45, s45, 0
	s_add_u32 s54, s54, 0x100
	s_addc_u32 s55, s55, 0
	s_cmp_gt_u32 s47, 29
	s_cbranch_scc0 .LBB0_209
	s_and_b64 vcc, exec, s[24:25]
	s_cbranch_vccz .LBB0_212
	s_barrier

; #define LAS __attribute__((address_space(3)))
; __device__ __forceinline__ unsigned cvt_pk_bf16(float lo, float hi) { unsigned r; asm("v_cvt_pk_bf16_f32 %0, %1, %2" : "=v"(r) : "v"(lo), "v"(hi)); return r; }
; __device__ __forceinline__ void tstore_sub(const f32x4 (&v)[4][2], bf16_t* dst  , LAS unsigned char* x, int fr, int fq, int lane) {
; #pragma unroll
;     for (int m = 0; m < 4; ++m)
; #pragma unroll
;         for (int n = 0; n < 2; ++n)
; #pragma unroll
;             for (int j = 0; j < 4; ++j) {
;                 const int ch = 8 * fq + 4 * n + j, tok = 16 * m + fr;
;                 const unsigned b = cvt_pk_bf16(v[m][n][j], 0.f);
;                 *(LAS unsigned short*)(x + ch * 128 + ((((tok >> 3) ^ fq) << 4) | ((tok & 7) << 1))) = (unsigned short)b;
;             }
;     LDS_WAIT();
; #pragma unroll
;     for (int i = 0; i < 4; ++i) {
;         const int q = lane + 64 * i, ch = q >> 3, tc = q & 7;
;         const u32x4 o = *(const LAS u32x4*)(x + ch * 128 + ((tc ^ ((ch >> 3) & 3)) << 4));
;         *(u32x4*)(dst + (size_t)ch * T + tc * 8) = o;
;     }
;     LDS_WAIT();
; }
;     __device__ __forceinline__ void operator()(const f32x4 (&acc)[2][2][4][2], const Unit& u, int wr, int wc, int fr, int fq, LAS unsigned char* xs, int wid, int lane) const {
;     ...
;             for (int ai = 0; ai < 2; ++ai)
; #pragma unroll
;                 for (int bj = 0; bj < 2; ++bj) {
;                     f32x4 v[4][2];
; #pragma unroll
;                     for (int m = 0; m < 4; ++m) { v[m][0] = acc[ai][bj][m][0] * rs[ai][m]; v[m][1] = acc[ai][bj][m][1] * rs[ai][m]; }
;                     if (ODD) {
;                         float* vss = (float*)(ws + OFF_VSS);
; #pragma unroll
;                         for (int m = 0; m < 4; ++m) {
;                             float s = 0.f;
; #pragma unroll
;                             for (int n = 0; n < 2; ++n) s += (v[m][n][0] * v[m][n][0] + v[m][n][1] * v[m][n][1]) + (v[m][n][2] * v[m][n][2] + v[m][n][3] * v[m][n][3]);
;                             s += __shfl_xor(s, 16); s += __shfl_xor(s, 32);
;                             if (fq == 0) vss[(size_t)(row0 + ai * 128 + m * 16 + fr) * 32 + (2 * (pn - 24) + bj) * 4 + wc] = s;
;                         }
;                     }
;                     tstore_sub(v, base + (size_t)(bj * 128 + wc * 32) * T + row0 + ai * 128, x, fr, fq, lane);
.LBB0_230:
	v_and_b32_e32 v233, 0x1c0, v254
	v_lshlrev_b32_e32 v233, 6, v233
	v_add_u32_e32 v233, 0x20000, v233
	v_and_b32_e32 v232, 63, v254
	v_lshl_add_u32 v232, v232, 2, v233
	ds_write_b32 v232, v143
	ds_write_b32 v232, v145 offset:256
	v_bfe_u32 v232, v254, 4, 2
	v_lshl_add_u32 v233, v232, 4, v233
	ds_read_b128 v[190:193], v233
	ds_read_b128 v[194:197], v233 offset:64
	ds_read_b128 v[198:201], v233 offset:128
	ds_read_b128 v[202:205], v233 offset:192
	ds_read_b128 v[206:209], v233 offset:256
	ds_read_b128 v[210:213], v233 offset:320
	ds_read_b128 v[214:217], v233 offset:384
	ds_read_b128 v[218:221], v233 offset:448
	v_and_b32_e32 v240, 0x1c0, v254
	v_lshlrev_b32_e32 v240, 6, v240
	v_add_u32_e32 v240, 0x20000, v240
	v_and_b32_e32 v232, 15, v254
	v_bfe_u32 v239, v254, 4, 2
	v_lshrrev_b32_e32 v241, 1, v239
	v_and_b32_e32 v235, 7, v232
	v_xor_b32_e32 v241, v241, v235
	v_lshlrev_b32_e32 v241, 4, v241
	v_and_b32_e32 v235, 1, v239
	v_lshl_add_u32 v241, v235, 3, v241
	v_lshl_add_u32 v241, v232, 8, v241
	v_add_u32_e32 v241, v240, v241
	v_and_b32_e32 v232, 63, v254
	v_lshrrev_b32_e32 v242, 4, v232
	v_and_b32_e32 v235, 7, v232
	v_xor_b32_e32 v242, v242, v235
	v_lshlrev_b32_e32 v242, 4, v242
	v_lshrrev_b32_e32 v236, 3, v232
	v_lshl_add_u32 v242, v236, 7, v242
	v_add_u32_e32 v242, v240, v242
	v_xor_b32_e32 v243, 64, v242
	v_and_b32_e32 v237, 1, v236
	v_lshlrev_b32_e32 v234, 1, v236
	v_sub_u32_e32 v234, v234, v237
	v_lshrrev_b32_e32 v237, 6, v254
	v_and_b32_e32 v237, 3, v237
	v_lshl_add_u32 v234, v237, 6, v234
	v_lshlrev_b32_e32 v234, 16, v234
	v_lshl_add_u32 v234, v235, 4, v234
	s_lshl_b32 s0, s54, 1
	s_add_u32 s18, s56, s0
	s_addc_u32 s19, s57, 0
	s_waitcnt lgkmcnt(0)
	v_mul_f32_e32 v235, v124, v190
	v_mul_f32_e32 v236, v125, v191
	v_mul_f32_e32 v237, v126, v192
	v_mul_f32_e32 v238, v127, v193
	v_cvt_pk_bf16_f32 v224, v235, v236
	v_cvt_pk_bf16_f32 v225, v237, v238
	ds_write_b64 v241, v[224:225]
	v_mul_f32_e32 v235, v120, v190
	v_mul_f32_e32 v236, v121, v191
	v_mul_f32_e32 v237, v122, v192
	v_mul_f32_e32 v238, v123, v193
	v_cvt_pk_bf16_f32 v226, v235, v236
	v_cvt_pk_bf16_f32 v227, v237, v238
	ds_write_b64 v241, v[226:227] offset:128
	v_xor_b32_e32 v239, 0x20, v241
	v_mul_f32_e32 v235, v108, v194
	v_mul_f32_e32 v236, v109, v195
	v_mul_f32_e32 v237, v110, v196
	v_mul_f32_e32 v238, v111, v197
	v_cvt_pk_bf16_f32 v228, v235, v236
	v_cvt_pk_bf16_f32 v229, v237, v238
	ds_write_b64 v239, v[228:229]
	v_mul_f32_e32 v235, v104, v194
	v_mul_f32_e32 v236, v105, v195
	v_mul_f32_e32 v237, v106, v196
	v_mul_f32_e32 v238, v107, v197
	v_cvt_pk_bf16_f32 v230, v235, v236
	v_cvt_pk_bf16_f32 v231, v237, v238
	ds_write_b64 v239, v[230:231] offset:128
	v_xor_b32_e32 v239, 0x40, v241
	v_mul_f32_e32 v235, v92, v198
	v_mul_f32_e32 v236, v93, v199
	v_mul_f32_e32 v237, v94, v200
	v_mul_f32_e32 v238, v95, v201
	v_cvt_pk_bf16_f32 v224, v235, v236
	v_cvt_pk_bf16_f32 v225, v237, v238
	ds_write_b64 v239, v[224:225]
	v_mul_f32_e32 v235, v88, v198
	v_mul_f32_e32 v236, v89, v199
	v_mul_f32_e32 v237, v90, v200
	v_mul_f32_e32 v238, v91, v201
	v_cvt_pk_bf16_f32 v226, v235, v236
	v_cvt_pk_bf16_f32 v227, v237, v238
	ds_write_b64 v239, v[226:227] offset:128
	v_xor_b32_e32 v239, 0x60, v241
	v_mul_f32_e32 v235, v76, v202
	v_mul_f32_e32 v236, v77, v203
	v_mul_f32_e32 v237, v78, v204
	v_mul_f32_e32 v238, v79, v205
	v_cvt_pk_bf16_f32 v228, v235, v236
	v_cvt_pk_bf16_f32 v229, v237, v238
	ds_write_b64 v239, v[228:229]
	v_mul_f32_e32 v235, v72, v202
	v_mul_f32_e32 v236, v73, v203
	v_mul_f32_e32 v237, v74, v204
	v_mul_f32_e32 v238, v75, v205
	v_cvt_pk_bf16_f32 v230, v235, v236
	v_cvt_pk_bf16_f32 v231, v237, v238
	ds_write_b64 v239, v[230:231] offset:128
	ds_read_b128 v[176:179], v242
	ds_read_b128 v[180:183], v243 offset:1024
	ds_read_b128 v[244:247], v242 offset:2048
	ds_read_b128 v[248:251], v243 offset:3072
	s_waitcnt lgkmcnt(3)
	s_add_u32 s58, s18, 0x0
	s_addc_u32 s59, s19, 0
	global_store_dwordx4 v234, v[176:179], s[58:59]
	s_waitcnt lgkmcnt(2)
	s_add_u32 s58, s18, 0x100000
	s_addc_u32 s59, s19, 0
	global_store_dwordx4 v234, v[180:183], s[58:59]
	s_waitcnt lgkmcnt(1)
	s_add_u32 s58, s18, 0x200000
	s_addc_u32 s59, s19, 0
	global_store_dwordx4 v234, v[244:247], s[58:59]
	s_waitcnt lgkmcnt(0)
	s_add_u32 s58, s18, 0x300000
	s_addc_u32 s59, s19, 0
	global_store_dwordx4 v234, v[248:251], s[58:59]
	v_mul_f32_e32 v235, v116, v190
	v_mul_f32_e32 v236, v117, v191
	v_mul_f32_e32 v237, v118, v192
	v_mul_f32_e32 v238, v119, v193
	v_cvt_pk_bf16_f32 v224, v235, v236
	v_cvt_pk_bf16_f32 v225, v237, v238
	ds_write_b64 v241, v[224:225]
	v_mul_f32_e32 v235, v112, v190
	v_mul_f32_e32 v236, v113, v191
	v_mul_f32_e32 v237, v114, v192
	v_mul_f32_e32 v238, v115, v193
	v_cvt_pk_bf16_f32 v226, v235, v236
	v_cvt_pk_bf16_f32 v227, v237, v238
	ds_write_b64 v241, v[226:227] offset:128
	v_xor_b32_e32 v239, 0x20, v241
	v_mul_f32_e32 v235, v100, v194
	v_mul_f32_e32 v236, v101, v195
	v_mul_f32_e32 v237, v102, v196
	v_mul_f32_e32 v238, v103, v197
	v_cvt_pk_bf16_f32 v228, v235, v236
	v_cvt_pk_bf16_f32 v229, v237, v238
	ds_write_b64 v239, v[228:229]
	v_mul_f32_e32 v235, v96, v194
	v_mul_f32_e32 v236, v97, v195
	v_mul_f32_e32 v237, v98, v196
	v_mul_f32_e32 v238, v99, v197
	v_cvt_pk_bf16_f32 v230, v235, v236
	v_cvt_pk_bf16_f32 v231, v237, v238
	ds_write_b64 v239, v[230:231] offset:128
	v_xor_b32_e32 v239, 0x40, v241
	v_mul_f32_e32 v235, v84, v198
	v_mul_f32_e32 v236, v85, v199
	v_mul_f32_e32 v237, v86, v200
	v_mul_f32_e32 v238, v87, v201
	v_cvt_pk_bf16_f32 v224, v235, v236
	v_cvt_pk_bf16_f32 v225, v237, v238
	ds_write_b64 v239, v[224:225]
	v_mul_f32_e32 v235, v80, v198
	v_mul_f32_e32 v236, v81, v199
	v_mul_f32_e32 v237, v82, v200
	v_mul_f32_e32 v238, v83, v201
	v_cvt_pk_bf16_f32 v226, v235, v236
	v_cvt_pk_bf16_f32 v227, v237, v238
	ds_write_b64 v239, v[226:227] offset:128
	v_xor_b32_e32 v239, 0x60, v241
	v_mul_f32_e32 v235, v68, v202
	v_mul_f32_e32 v236, v69, v203
	v_mul_f32_e32 v237, v70, v204
	v_mul_f32_e32 v238, v71, v205
	v_cvt_pk_bf16_f32 v228, v235, v236
	v_cvt_pk_bf16_f32 v229, v237, v238
	ds_write_b64 v239, v[228:229]
	v_mul_f32_e32 v235, v64, v202
	v_mul_f32_e32 v236, v65, v203
	v_mul_f32_e32 v237, v66, v204
	v_mul_f32_e32 v238, v67, v205
	v_cvt_pk_bf16_f32 v230, v235, v236
	v_cvt_pk_bf16_f32 v231, v237, v238
	ds_write_b64 v239, v[230:231] offset:128
	ds_read_b128 v[176:179], v242
	ds_read_b128 v[180:183], v243 offset:1024
	ds_read_b128 v[244:247], v242 offset:2048
	ds_read_b128 v[248:251], v243 offset:3072
	s_waitcnt lgkmcnt(3)
; #define LAS __attribute__((address_space(3)))
; __device__ __forceinline__ unsigned cvt_pk_bf16(float lo, float hi) { unsigned r; asm("v_cvt_pk_bf16_f32 %0, %1, %2" : "=v"(r) : "v"(lo), "v"(hi)); return r; }
; __device__ __forceinline__ void tstore_sub(const f32x4 (&v)[4][2], bf16_t* dst  , LAS unsigned char* x, int fr, int fq, int lane) {
; #pragma unroll
;     for (int m = 0; m < 4; ++m)
; #pragma unroll
;         for (int n = 0; n < 2; ++n)
; #pragma unroll
;             for (int j = 0; j < 4; ++j) {
;                 const int ch = 8 * fq + 4 * n + j, tok = 16 * m + fr;
;                 const unsigned b = cvt_pk_bf16(v[m][n][j], 0.f);
;                 *(LAS unsigned short*)(x + ch * 128 + ((((tok >> 3) ^ fq) << 4) | ((tok & 7) << 1))) = (unsigned short)b;
;             }
;     LDS_WAIT();
; #pragma unroll
;     for (int i = 0; i < 4; ++i) {
;         const int q = lane + 64 * i, ch = q >> 3, tc = q & 7;
;         const u32x4 o = *(const LAS u32x4*)(x + ch * 128 + ((tc ^ ((ch >> 3) & 3)) << 4));
;         *(u32x4*)(dst + (size_t)ch * T + tc * 8) = o;
;     }
;     LDS_WAIT();
; }
;     __device__ __forceinline__ void operator()(const f32x4 (&acc)[2][2][4][2], const Unit& u, int wr, int wc, int fr, int fq, LAS unsigned char* xs, int wid, int lane) const {
;     ...
;             for (int ai = 0; ai < 2; ++ai)
; #pragma unroll
;                 for (int bj = 0; bj < 2; ++bj) {
;                     f32x4 v[4][2];
; #pragma unroll
;                     for (int m = 0; m < 4; ++m) { v[m][0] = acc[ai][bj][m][0] * rs[ai][m]; v[m][1] = acc[ai][bj][m][1] * rs[ai][m]; }
;                     if (ODD) {
;                         float* vss = (float*)(ws + OFF_VSS);
; #pragma unroll
;                         for (int m = 0; m < 4; ++m) {
;                             float s = 0.f;
; #pragma unroll
;                             for (int n = 0; n < 2; ++n) s += (v[m][n][0] * v[m][n][0] + v[m][n][1] * v[m][n][1]) + (v[m][n][2] * v[m][n][2] + v[m][n][3] * v[m][n][3]);
;                             s += __shfl_xor(s, 16); s += __shfl_xor(s, 32);
;                             if (fq == 0) vss[(size_t)(row0 + ai * 128 + m * 16 + fr) * 32 + (2 * (pn - 24) + bj) * 4 + wc] = s;
;                         }
;                     }
;                     tstore_sub(v, base + (size_t)(bj * 128 + wc * 32) * T + row0 + ai * 128, x, fr, fq, lane);
	s_add_u32 s58, s18, 0x20000
	s_addc_u32 s59, s19, 0
	global_store_dwordx4 v234, v[176:179], s[58:59]
	s_waitcnt lgkmcnt(2)
	s_add_u32 s58, s18, 0x120000
	s_addc_u32 s59, s19, 0
	global_store_dwordx4 v234, v[180:183], s[58:59]
	s_waitcnt lgkmcnt(1)
	s_add_u32 s58, s18, 0x220000
	s_addc_u32 s59, s19, 0
	global_store_dwordx4 v234, v[244:247], s[58:59]
	s_waitcnt lgkmcnt(0)
	s_add_u32 s58, s18, 0x320000
	s_addc_u32 s59, s19, 0
	global_store_dwordx4 v234, v[248:251], s[58:59]
	v_mul_f32_e32 v235, v60, v206
	v_mul_f32_e32 v236, v61, v207
	v_mul_f32_e32 v237, v62, v208
	v_mul_f32_e32 v238, v63, v209
	v_cvt_pk_bf16_f32 v224, v235, v236
	v_cvt_pk_bf16_f32 v225, v237, v238
	ds_write_b64 v241, v[224:225]
	v_mul_f32_e32 v235, v56, v206
	v_mul_f32_e32 v236, v57, v207
	v_mul_f32_e32 v237, v58, v208
	v_mul_f32_e32 v238, v59, v209
	v_cvt_pk_bf16_f32 v226, v235, v236
	v_cvt_pk_bf16_f32 v227, v237, v238
	ds_write_b64 v241, v[226:227] offset:128
	v_xor_b32_e32 v239, 0x20, v241
	v_mul_f32_e32 v235, v44, v210
	v_mul_f32_e32 v236, v45, v211
	v_mul_f32_e32 v237, v46, v212
	v_mul_f32_e32 v238, v47, v213
	v_cvt_pk_bf16_f32 v228, v235, v236
	v_cvt_pk_bf16_f32 v229, v237, v238
	ds_write_b64 v239, v[228:229]
	v_mul_f32_e32 v235, v40, v210
	v_mul_f32_e32 v236, v41, v211
	v_mul_f32_e32 v237, v42, v212
	v_mul_f32_e32 v238, v43, v213
	v_cvt_pk_bf16_f32 v230, v235, v236
	v_cvt_pk_bf16_f32 v231, v237, v238
	ds_write_b64 v239, v[230:231] offset:128
	v_xor_b32_e32 v239, 0x40, v241
	v_mul_f32_e32 v235, v28, v214
	v_mul_f32_e32 v236, v29, v215
	v_mul_f32_e32 v237, v30, v216
	v_mul_f32_e32 v238, v31, v217
	v_cvt_pk_bf16_f32 v224, v235, v236
	v_cvt_pk_bf16_f32 v225, v237, v238
	ds_write_b64 v239, v[224:225]
	v_mul_f32_e32 v235, v24, v214
	v_mul_f32_e32 v236, v25, v215
	v_mul_f32_e32 v237, v26, v216
	v_mul_f32_e32 v238, v27, v217
	v_cvt_pk_bf16_f32 v226, v235, v236
	v_cvt_pk_bf16_f32 v227, v237, v238
	ds_write_b64 v239, v[226:227] offset:128
	v_xor_b32_e32 v239, 0x60, v241
	v_mul_f32_e32 v235, v12, v218
	v_mul_f32_e32 v236, v13, v219
	v_mul_f32_e32 v237, v14, v220
	v_mul_f32_e32 v238, v15, v221
	v_cvt_pk_bf16_f32 v228, v235, v236
	v_cvt_pk_bf16_f32 v229, v237, v238
	ds_write_b64 v239, v[228:229]
	v_mul_f32_e32 v235, v8, v218
	v_mul_f32_e32 v236, v9, v219
	v_mul_f32_e32 v237, v10, v220
	v_mul_f32_e32 v238, v11, v221
	v_cvt_pk_bf16_f32 v230, v235, v236
	v_cvt_pk_bf16_f32 v231, v237, v238
	ds_write_b64 v239, v[230:231] offset:128
	ds_read_b128 v[176:179], v242
	ds_read_b128 v[180:183], v243 offset:1024
	ds_read_b128 v[244:247], v242 offset:2048
	ds_read_b128 v[248:251], v243 offset:3072
	s_waitcnt lgkmcnt(3)
	s_add_u32 s58, s18, 0x100
	s_addc_u32 s59, s19, 0
	global_store_dwordx4 v234, v[176:179], s[58:59]
	s_waitcnt lgkmcnt(2)
	s_add_u32 s58, s18, 0x100100
	s_addc_u32 s59, s19, 0
	global_store_dwordx4 v234, v[180:183], s[58:59]
	s_waitcnt lgkmcnt(1)
	s_add_u32 s58, s18, 0x200100
	s_addc_u32 s59, s19, 0
	global_store_dwordx4 v234, v[244:247], s[58:59]
	s_waitcnt lgkmcnt(0)
	s_add_u32 s58, s18, 0x300100
	s_addc_u32 s59, s19, 0
	global_store_dwordx4 v234, v[248:251], s[58:59]
	v_mul_f32_e32 v235, v52, v206
	v_mul_f32_e32 v236, v53, v207
	v_mul_f32_e32 v237, v54, v208
	v_mul_f32_e32 v238, v55, v209
	v_cvt_pk_bf16_f32 v224, v235, v236
	v_cvt_pk_bf16_f32 v225, v237, v238
	ds_write_b64 v241, v[224:225]
	v_mul_f32_e32 v235, v48, v206
	v_mul_f32_e32 v236, v49, v207
	v_mul_f32_e32 v237, v50, v208
	v_mul_f32_e32 v238, v51, v209
	v_cvt_pk_bf16_f32 v226, v235, v236
	v_cvt_pk_bf16_f32 v227, v237, v238
	ds_write_b64 v241, v[226:227] offset:128
	v_xor_b32_e32 v239, 0x20, v241
	v_mul_f32_e32 v235, v36, v210
	v_mul_f32_e32 v236, v37, v211
	v_mul_f32_e32 v237, v38, v212
	v_mul_f32_e32 v238, v39, v213
	v_cvt_pk_bf16_f32 v228, v235, v236
	v_cvt_pk_bf16_f32 v229, v237, v238
	ds_write_b64 v239, v[228:229]
	v_mul_f32_e32 v235, v32, v210
	v_mul_f32_e32 v236, v33, v211
	v_mul_f32_e32 v237, v34, v212
	v_mul_f32_e32 v238, v35, v213
	v_cvt_pk_bf16_f32 v230, v235, v236
	v_cvt_pk_bf16_f32 v231, v237, v238
	ds_write_b64 v239, v[230:231] offset:128
	v_xor_b32_e32 v239, 0x40, v241
	v_mul_f32_e32 v235, v20, v214
	v_mul_f32_e32 v236, v21, v215
	v_mul_f32_e32 v237, v22, v216
	v_mul_f32_e32 v238, v23, v217
	v_cvt_pk_bf16_f32 v224, v235, v236
	v_cvt_pk_bf16_f32 v225, v237, v238
	ds_write_b64 v239, v[224:225]
	v_mul_f32_e32 v235, v16, v214
	v_mul_f32_e32 v236, v17, v215
	v_mul_f32_e32 v237, v18, v216
	v_mul_f32_e32 v238, v19, v217
	v_cvt_pk_bf16_f32 v226, v235, v236
	v_cvt_pk_bf16_f32 v227, v237, v238
	ds_write_b64 v239, v[226:227] offset:128
	v_xor_b32_e32 v239, 0x60, v241
	v_mul_f32_e32 v235, v4, v218
	v_mul_f32_e32 v236, v5, v219
	v_mul_f32_e32 v237, v6, v220
	v_mul_f32_e32 v238, v7, v221
	v_cvt_pk_bf16_f32 v228, v235, v236
	v_cvt_pk_bf16_f32 v229, v237, v238
	ds_write_b64 v239, v[228:229]
	v_mul_f32_e32 v235, v0, v218
	v_mul_f32_e32 v236, v1, v219
	v_mul_f32_e32 v237, v2, v220
	v_mul_f32_e32 v238, v3, v221
	v_cvt_pk_bf16_f32 v230, v235, v236
	v_cvt_pk_bf16_f32 v231, v237, v238
	ds_write_b64 v239, v[230:231] offset:128
	ds_read_b128 v[176:179], v242
	ds_read_b128 v[180:183], v243 offset:1024
	ds_read_b128 v[244:247], v242 offset:2048
	ds_read_b128 v[248:251], v243 offset:3072
	s_waitcnt lgkmcnt(3)
	s_add_u32 s58, s18, 0x20100
	s_addc_u32 s59, s19, 0
	global_store_dwordx4 v234, v[176:179], s[58:59]
	s_waitcnt lgkmcnt(2)
	s_add_u32 s58, s18, 0x120100
	s_addc_u32 s59, s19, 0
	global_store_dwordx4 v234, v[180:183], s[58:59]
	s_waitcnt lgkmcnt(1)
	s_add_u32 s58, s18, 0x220100
	s_addc_u32 s59, s19, 0
	global_store_dwordx4 v234, v[244:247], s[58:59]
	s_waitcnt lgkmcnt(0)
	s_add_u32 s58, s18, 0x320100
	s_addc_u32 s59, s19, 0
	global_store_dwordx4 v234, v[248:251], s[58:59]
	s_branch .LBB0_216
; __device__ __forceinline__ unsigned cvt_pk_bf16(float lo, float hi) { unsigned r; asm("v_cvt_pk_bf16_f32 %0, %1, %2" : "=v"(r) : "v"(lo), "v"(hi)); return r; }
;     __device__ __forceinline__ void operator()(const f32x4 (&acc)[2][2][4][2], const Unit& u, int wr, int wc, int fr, int fq, LAS unsigned char* xs, int wid, int lane) const {
;     ...
;         for (int ai = 0; ai < 2; ++ai) {
;             const f32x4* pp = (const f32x4*)(rss + (size_t)(row0 + ai * 128 + lane) * 8);
;             const f32x4 v0 = pp[0], v1 = pp[1];
;             const float s = ((v0[0] + v0[1]) + (v0[2] + v0[3])) + ((v1[0] + v1[1]) + (v1[2] + v1[3]));
;             const float r = rsqrtf(s * (1.f / D) + EPS);
; #pragma unroll
;             for (int m = 0; m < 4; ++m) rs[ai][m] = __shfl(r, 16 * m + fr);
;         }
;     ...
;         if (mode == 0) {
; #pragma unroll
;             for (int ai = 0; ai < 2; ++ai)
; #pragma unroll
;                 for (int m = 0; m < 4; ++m) {
;                     const float r = rs[ai][m];
;                     bf16_t* rowp = base + (size_t)(row0 + ai * 128 + m * 16 + fr) * ldc + wc * 32 + 8 * fq;
; #pragma unroll
;                     for (int bj = 0; bj < 2; ++bj) { const f32x4 v0 = acc[ai][bj][m][0] * r, v1 = acc[ai][bj][m][1] * r;
;                         u32x4 w; w.x = cvt_pk_bf16(v0[0], v0[1]); w.y = cvt_pk_bf16(v0[2], v0[3]); w.z = cvt_pk_bf16(v1[0], v1[1]); w.w = cvt_pk_bf16(v1[2], v1[3]);
;                         *(u32x4*)(rowp + bj * 128) = w; }
;                     __builtin_amdgcn_sched_barrier(0);
;                 }
.LBB0_231:
	v_and_b32_e32 v233, 0x1c0, v254
	v_lshlrev_b32_e32 v233, 6, v233
	v_add_u32_e32 v233, 0x20000, v233
	v_and_b32_e32 v232, 63, v254
	v_lshl_add_u32 v232, v232, 2, v233
	ds_write_b32 v232, v143
	ds_write_b32 v232, v145 offset:256
	v_bfe_u32 v232, v254, 4, 2
	v_lshl_add_u32 v233, v232, 4, v233
	ds_read_b128 v[190:193], v233
	ds_read_b128 v[194:197], v233 offset:64
	ds_read_b128 v[198:201], v233 offset:128
	ds_read_b128 v[202:205], v233 offset:192
	ds_read_b128 v[206:209], v233 offset:256
	ds_read_b128 v[210:213], v233 offset:320
	ds_read_b128 v[214:217], v233 offset:384
	ds_read_b128 v[218:221], v233 offset:448
	v_bfe_u32 v234, v254, 4, 2
	v_lshlrev_b32_e32 v234, 2, v234
	v_mul_lo_u32 v234, v234, s6
	v_and_b32_e32 v232, 15, v254
	v_lshl_add_u32 v234, v232, 2, v234
	v_lshrrev_b32_e32 v232, 6, v254
	v_and_b32_e32 v232, 3, v232
	v_lshl_add_u32 v234, v232, 6, v234
	v_lshlrev_b32_e32 v234, 1, v234
	s_mul_i32 s0, s54, s6
	s_lshl_b32 s0, s0, 1
	s_add_u32 s18, s56, s0
	s_addc_u32 s19, s57, 0
	s_lshl_b32 s20, s6, 1
	s_waitcnt lgkmcnt(0)
	v_mul_f32_e32 v235, v124, v190
	v_mul_f32_e32 v236, v120, v190
	v_mul_f32_e32 v237, v116, v190
	v_mul_f32_e32 v238, v112, v190
	v_cvt_pk_bf16_f32 v224, v235, v236
	v_cvt_pk_bf16_f32 v225, v237, v238
	global_store_dwordx2 v234, v[224:225], s[18:19]
	v_mul_f32_e32 v235, v125, v191
	v_mul_f32_e32 v236, v121, v191
	v_mul_f32_e32 v237, v117, v191
	v_mul_f32_e32 v238, v113, v191
	v_cvt_pk_bf16_f32 v226, v235, v236
	v_cvt_pk_bf16_f32 v227, v237, v238
	s_mul_i32 s0, s20, 0x1
	s_add_u32 s60, s18, s0
	s_addc_u32 s61, s19, 0
	global_store_dwordx2 v234, v[226:227], s[60:61]
	v_mul_f32_e32 v235, v126, v192
	v_mul_f32_e32 v236, v122, v192
	v_mul_f32_e32 v237, v118, v192
	v_mul_f32_e32 v238, v114, v192
	v_cvt_pk_bf16_f32 v228, v235, v236
	v_cvt_pk_bf16_f32 v229, v237, v238
	s_mul_i32 s0, s20, 0x2
	s_add_u32 s58, s18, s0
	s_addc_u32 s59, s19, 0
	global_store_dwordx2 v234, v[228:229], s[58:59]
	v_mul_f32_e32 v235, v127, v193
	v_mul_f32_e32 v236, v123, v193
	v_mul_f32_e32 v237, v119, v193
	v_mul_f32_e32 v238, v115, v193
	v_cvt_pk_bf16_f32 v230, v235, v236
	v_cvt_pk_bf16_f32 v231, v237, v238
	s_mul_i32 s0, s20, 0x3
	s_add_u32 s60, s18, s0
	s_addc_u32 s61, s19, 0
	global_store_dwordx2 v234, v[230:231], s[60:61]
	v_mul_f32_e32 v235, v108, v194
	v_mul_f32_e32 v236, v104, v194
	v_mul_f32_e32 v237, v100, v194
	v_mul_f32_e32 v238, v96, v194
	v_cvt_pk_bf16_f32 v224, v235, v236
	v_cvt_pk_bf16_f32 v225, v237, v238
	s_mul_i32 s0, s20, 0x10
	s_add_u32 s58, s18, s0
	s_addc_u32 s59, s19, 0
	global_store_dwordx2 v234, v[224:225], s[58:59]
	v_mul_f32_e32 v235, v109, v195
	v_mul_f32_e32 v236, v105, v195
	v_mul_f32_e32 v237, v101, v195
	v_mul_f32_e32 v238, v97, v195
	v_cvt_pk_bf16_f32 v226, v235, v236
	v_cvt_pk_bf16_f32 v227, v237, v238
	s_mul_i32 s0, s20, 0x11
	s_add_u32 s60, s18, s0
	s_addc_u32 s61, s19, 0
	global_store_dwordx2 v234, v[226:227], s[60:61]
	v_mul_f32_e32 v235, v110, v196
	v_mul_f32_e32 v236, v106, v196
	v_mul_f32_e32 v237, v102, v196
	v_mul_f32_e32 v238, v98, v196
	v_cvt_pk_bf16_f32 v228, v235, v236
	v_cvt_pk_bf16_f32 v229, v237, v238
	s_mul_i32 s0, s20, 0x12
	s_add_u32 s58, s18, s0
	s_addc_u32 s59, s19, 0
	global_store_dwordx2 v234, v[228:229], s[58:59]
	v_mul_f32_e32 v235, v111, v197
	v_mul_f32_e32 v236, v107, v197
	v_mul_f32_e32 v237, v103, v197
	v_mul_f32_e32 v238, v99, v197
	v_cvt_pk_bf16_f32 v230, v235, v236
	v_cvt_pk_bf16_f32 v231, v237, v238
	s_mul_i32 s0, s20, 0x13
	s_add_u32 s60, s18, s0
	s_addc_u32 s61, s19, 0
	global_store_dwordx2 v234, v[230:231], s[60:61]
	v_mul_f32_e32 v235, v92, v198
	v_mul_f32_e32 v236, v88, v198
	v_mul_f32_e32 v237, v84, v198
	v_mul_f32_e32 v238, v80, v198
	v_cvt_pk_bf16_f32 v224, v235, v236
	v_cvt_pk_bf16_f32 v225, v237, v238
	s_mul_i32 s0, s20, 0x20
	s_add_u32 s58, s18, s0
	s_addc_u32 s59, s19, 0
	global_store_dwordx2 v234, v[224:225], s[58:59]
	v_mul_f32_e32 v235, v93, v199
	v_mul_f32_e32 v236, v89, v199
	v_mul_f32_e32 v237, v85, v199
	v_mul_f32_e32 v238, v81, v199
	v_cvt_pk_bf16_f32 v226, v235, v236
	v_cvt_pk_bf16_f32 v227, v237, v238
	s_mul_i32 s0, s20, 0x21
	s_add_u32 s60, s18, s0
	s_addc_u32 s61, s19, 0
	global_store_dwordx2 v234, v[226:227], s[60:61]
	v_mul_f32_e32 v235, v94, v200
	v_mul_f32_e32 v236, v90, v200
	v_mul_f32_e32 v237, v86, v200
	v_mul_f32_e32 v238, v82, v200
	v_cvt_pk_bf16_f32 v228, v235, v236
	v_cvt_pk_bf16_f32 v229, v237, v238
	s_mul_i32 s0, s20, 0x22
	s_add_u32 s58, s18, s0
	s_addc_u32 s59, s19, 0
	global_store_dwordx2 v234, v[228:229], s[58:59]
	v_mul_f32_e32 v235, v95, v201
	v_mul_f32_e32 v236, v91, v201
	v_mul_f32_e32 v237, v87, v201
	v_mul_f32_e32 v238, v83, v201
	v_cvt_pk_bf16_f32 v230, v235, v236
	v_cvt_pk_bf16_f32 v231, v237, v238
	s_mul_i32 s0, s20, 0x23
	s_add_u32 s60, s18, s0
	s_addc_u32 s61, s19, 0
	global_store_dwordx2 v234, v[230:231], s[60:61]
	v_mul_f32_e32 v235, v76, v202
	v_mul_f32_e32 v236, v72, v202
	v_mul_f32_e32 v237, v68, v202
	v_mul_f32_e32 v238, v64, v202
	v_cvt_pk_bf16_f32 v224, v235, v236
	v_cvt_pk_bf16_f32 v225, v237, v238
	s_mul_i32 s0, s20, 0x30
	s_add_u32 s58, s18, s0
	s_addc_u32 s59, s19, 0
	global_store_dwordx2 v234, v[224:225], s[58:59]
	v_mul_f32_e32 v235, v77, v203
	v_mul_f32_e32 v236, v73, v203
	v_mul_f32_e32 v237, v69, v203
	v_mul_f32_e32 v238, v65, v203
	v_cvt_pk_bf16_f32 v226, v235, v236
	v_cvt_pk_bf16_f32 v227, v237, v238
	s_mul_i32 s0, s20, 0x31
	s_add_u32 s60, s18, s0
	s_addc_u32 s61, s19, 0
	global_store_dwordx2 v234, v[226:227], s[60:61]
	v_mul_f32_e32 v235, v78, v204
	v_mul_f32_e32 v236, v74, v204
	v_mul_f32_e32 v237, v70, v204
	v_mul_f32_e32 v238, v66, v204
	v_cvt_pk_bf16_f32 v228, v235, v236
; __device__ __forceinline__ unsigned cvt_pk_bf16(float lo, float hi) { unsigned r; asm("v_cvt_pk_bf16_f32 %0, %1, %2" : "=v"(r) : "v"(lo), "v"(hi)); return r; }
;     __device__ __forceinline__ void operator()(const f32x4 (&acc)[2][2][4][2], const Unit& u, int wr, int wc, int fr, int fq, LAS unsigned char* xs, int wid, int lane) const {
;     ...
;         if (mode == 0) {
; #pragma unroll
;             for (int ai = 0; ai < 2; ++ai)
; #pragma unroll
;                 for (int m = 0; m < 4; ++m) {
;                     const float r = rs[ai][m];
;                     bf16_t* rowp = base + (size_t)(row0 + ai * 128 + m * 16 + fr) * ldc + wc * 32 + 8 * fq;
; #pragma unroll
;                     for (int bj = 0; bj < 2; ++bj) { const f32x4 v0 = acc[ai][bj][m][0] * r, v1 = acc[ai][bj][m][1] * r;
;                         u32x4 w; w.x = cvt_pk_bf16(v0[0], v0[1]); w.y = cvt_pk_bf16(v0[2], v0[3]); w.z = cvt_pk_bf16(v1[0], v1[1]); w.w = cvt_pk_bf16(v1[2], v1[3]);
;                         *(u32x4*)(rowp + bj * 128) = w; }
;                     __builtin_amdgcn_sched_barrier(0);
;                 }
	v_cvt_pk_bf16_f32 v229, v237, v238
	s_mul_i32 s0, s20, 0x32
	s_add_u32 s58, s18, s0
	s_addc_u32 s59, s19, 0
	global_store_dwordx2 v234, v[228:229], s[58:59]
	v_mul_f32_e32 v235, v79, v205
	v_mul_f32_e32 v236, v75, v205
	v_mul_f32_e32 v237, v71, v205
	v_mul_f32_e32 v238, v67, v205
	v_cvt_pk_bf16_f32 v230, v235, v236
	v_cvt_pk_bf16_f32 v231, v237, v238
	s_mul_i32 s0, s20, 0x33
	s_add_u32 s60, s18, s0
	s_addc_u32 s61, s19, 0
	global_store_dwordx2 v234, v[230:231], s[60:61]
	v_mul_f32_e32 v235, v60, v206
	v_mul_f32_e32 v236, v56, v206
	v_mul_f32_e32 v237, v52, v206
	v_mul_f32_e32 v238, v48, v206
	v_cvt_pk_bf16_f32 v224, v235, v236
	v_cvt_pk_bf16_f32 v225, v237, v238
	s_mul_i32 s0, s20, 0x80
	s_add_u32 s58, s18, s0
	s_addc_u32 s59, s19, 0
	global_store_dwordx2 v234, v[224:225], s[58:59]
	v_mul_f32_e32 v235, v61, v207
	v_mul_f32_e32 v236, v57, v207
	v_mul_f32_e32 v237, v53, v207
	v_mul_f32_e32 v238, v49, v207
	v_cvt_pk_bf16_f32 v226, v235, v236
	v_cvt_pk_bf16_f32 v227, v237, v238
	s_mul_i32 s0, s20, 0x81
	s_add_u32 s60, s18, s0
	s_addc_u32 s61, s19, 0
	global_store_dwordx2 v234, v[226:227], s[60:61]
	v_mul_f32_e32 v235, v62, v208
	v_mul_f32_e32 v236, v58, v208
	v_mul_f32_e32 v237, v54, v208
	v_mul_f32_e32 v238, v50, v208
	v_cvt_pk_bf16_f32 v228, v235, v236
	v_cvt_pk_bf16_f32 v229, v237, v238
	s_mul_i32 s0, s20, 0x82
	s_add_u32 s58, s18, s0
	s_addc_u32 s59, s19, 0
	global_store_dwordx2 v234, v[228:229], s[58:59]
	v_mul_f32_e32 v235, v63, v209
	v_mul_f32_e32 v236, v59, v209
	v_mul_f32_e32 v237, v55, v209
	v_mul_f32_e32 v238, v51, v209
	v_cvt_pk_bf16_f32 v230, v235, v236
	v_cvt_pk_bf16_f32 v231, v237, v238
	s_mul_i32 s0, s20, 0x83
	s_add_u32 s60, s18, s0
	s_addc_u32 s61, s19, 0
	global_store_dwordx2 v234, v[230:231], s[60:61]
	v_mul_f32_e32 v235, v44, v210
	v_mul_f32_e32 v236, v40, v210
	v_mul_f32_e32 v237, v36, v210
	v_mul_f32_e32 v238, v32, v210
	v_cvt_pk_bf16_f32 v224, v235, v236
	v_cvt_pk_bf16_f32 v225, v237, v238
	s_mul_i32 s0, s20, 0x90
	s_add_u32 s58, s18, s0
	s_addc_u32 s59, s19, 0
	global_store_dwordx2 v234, v[224:225], s[58:59]
	v_mul_f32_e32 v235, v45, v211
	v_mul_f32_e32 v236, v41, v211
	v_mul_f32_e32 v237, v37, v211
	v_mul_f32_e32 v238, v33, v211
	v_cvt_pk_bf16_f32 v226, v235, v236
	v_cvt_pk_bf16_f32 v227, v237, v238
	s_mul_i32 s0, s20, 0x91
	s_add_u32 s60, s18, s0
	s_addc_u32 s61, s19, 0
	global_store_dwordx2 v234, v[226:227], s[60:61]
	v_mul_f32_e32 v235, v46, v212
	v_mul_f32_e32 v236, v42, v212
	v_mul_f32_e32 v237, v38, v212
	v_mul_f32_e32 v238, v34, v212
	v_cvt_pk_bf16_f32 v228, v235, v236
	v_cvt_pk_bf16_f32 v229, v237, v238
	s_mul_i32 s0, s20, 0x92
	s_add_u32 s58, s18, s0
	s_addc_u32 s59, s19, 0
	global_store_dwordx2 v234, v[228:229], s[58:59]
	v_mul_f32_e32 v235, v47, v213
	v_mul_f32_e32 v236, v43, v213
	v_mul_f32_e32 v237, v39, v213
	v_mul_f32_e32 v238, v35, v213
	v_cvt_pk_bf16_f32 v230, v235, v236
	v_cvt_pk_bf16_f32 v231, v237, v238
	s_mul_i32 s0, s20, 0x93
	s_add_u32 s60, s18, s0
	s_addc_u32 s61, s19, 0
	global_store_dwordx2 v234, v[230:231], s[60:61]
	v_mul_f32_e32 v235, v28, v214
	v_mul_f32_e32 v236, v24, v214
	v_mul_f32_e32 v237, v20, v214
	v_mul_f32_e32 v238, v16, v214
	v_cvt_pk_bf16_f32 v224, v235, v236
	v_cvt_pk_bf16_f32 v225, v237, v238
	s_mul_i32 s0, s20, 0xa0
	s_add_u32 s58, s18, s0
	s_addc_u32 s59, s19, 0
	global_store_dwordx2 v234, v[224:225], s[58:59]
	v_mul_f32_e32 v235, v29, v215
	v_mul_f32_e32 v236, v25, v215
	v_mul_f32_e32 v237, v21, v215
	v_mul_f32_e32 v238, v17, v215
	v_cvt_pk_bf16_f32 v226, v235, v236
	v_cvt_pk_bf16_f32 v227, v237, v238
	s_mul_i32 s0, s20, 0xa1
	s_add_u32 s60, s18, s0
	s_addc_u32 s61, s19, 0
	global_store_dwordx2 v234, v[226:227], s[60:61]
	v_mul_f32_e32 v235, v30, v216
	v_mul_f32_e32 v236, v26, v216
	v_mul_f32_e32 v237, v22, v216
	v_mul_f32_e32 v238, v18, v216
	v_cvt_pk_bf16_f32 v228, v235, v236
	v_cvt_pk_bf16_f32 v229, v237, v238
	s_mul_i32 s0, s20, 0xa2
	s_add_u32 s58, s18, s0
	s_addc_u32 s59, s19, 0
	global_store_dwordx2 v234, v[228:229], s[58:59]
	v_mul_f32_e32 v235, v31, v217
	v_mul_f32_e32 v236, v27, v217
	v_mul_f32_e32 v237, v23, v217
	v_mul_f32_e32 v238, v19, v217
	v_cvt_pk_bf16_f32 v230, v235, v236
	v_cvt_pk_bf16_f32 v231, v237, v238
	s_mul_i32 s0, s20, 0xa3
	s_add_u32 s60, s18, s0
	s_addc_u32 s61, s19, 0
	global_store_dwordx2 v234, v[230:231], s[60:61]
	v_mul_f32_e32 v235, v12, v218
	v_mul_f32_e32 v236, v8, v218
	v_mul_f32_e32 v237, v4, v218
	v_mul_f32_e32 v238, v0, v218
	v_cvt_pk_bf16_f32 v224, v235, v236
	v_cvt_pk_bf16_f32 v225, v237, v238
	s_mul_i32 s0, s20, 0xb0
	s_add_u32 s58, s18, s0
	s_addc_u32 s59, s19, 0
	global_store_dwordx2 v234, v[224:225], s[58:59]
	v_mul_f32_e32 v235, v13, v219
	v_mul_f32_e32 v236, v9, v219
	v_mul_f32_e32 v237, v5, v219
	v_mul_f32_e32 v238, v1, v219
	v_cvt_pk_bf16_f32 v226, v235, v236
	v_cvt_pk_bf16_f32 v227, v237, v238
	s_mul_i32 s0, s20, 0xb1
	s_add_u32 s60, s18, s0
	s_addc_u32 s61, s19, 0
	global_store_dwordx2 v234, v[226:227], s[60:61]
	v_mul_f32_e32 v235, v14, v220
	v_mul_f32_e32 v236, v10, v220
	v_mul_f32_e32 v237, v6, v220
	v_mul_f32_e32 v238, v2, v220
	v_cvt_pk_bf16_f32 v228, v235, v236
	v_cvt_pk_bf16_f32 v229, v237, v238
	s_mul_i32 s0, s20, 0xb2
	s_add_u32 s58, s18, s0
	s_addc_u32 s59, s19, 0
	global_store_dwordx2 v234, v[228:229], s[58:59]
	v_mul_f32_e32 v235, v15, v221
	v_mul_f32_e32 v236, v11, v221
	v_mul_f32_e32 v237, v7, v221
	v_mul_f32_e32 v238, v3, v221
	v_cvt_pk_bf16_f32 v230, v235, v236
	v_cvt_pk_bf16_f32 v231, v237, v238
	s_mul_i32 s0, s20, 0xb3
	s_add_u32 s60, s18, s0
	s_addc_u32 s61, s19, 0
	global_store_dwordx2 v234, v[230:231], s[60:61]
	s_andn2_b64 vcc, exec, s[4:5]
	s_mov_b64 s[4:5], -1
	s_cbranch_vccnz .LBB0_205

; #define PG8_STAGE(bufoff, gbase, voff) do { _Pragma("unroll") for (int _i = 0; _i < 2; ++_i) \
;         __builtin_amdgcn_global_load_lds((const unsigned*)((const char*)(gbase) + (voff)[_i]), (LAS unsigned*)(lds + (bufoff) + ldsw + _i * 8192), 16, 0, 0); } while (0)
; #define PG8_WAIT_V(n) asm volatile("s_waitcnt vmcnt(" #n ")" ::: "memory")
; #define PG8_BAR __builtin_amdgcn_s_barrier()
; template <class Epi, class Sched>
; __device__ __forceinline__ void gemm_phase(LAS unsigned char* lds, const int K, const int lda, const int ldb, const Sched& S, const Epi& E) {
;     int tid = threadIdx.x; asm volatile("" : "+v"(tid));
;     const int wid = __builtin_amdgcn_readfirstlane(tid >> 6), lane = tid & 63, wr = wid >> 2, wc = wid & 3, fr = lane & 15, fq = lane >> 4;
;     const int nt = K / BK;
;     unsigned voffA[2], voffB[2];
; #pragma unroll
;     for (int i = 0; i < 2; ++i) { int R, C; stage_rc(tid * 16 + i * 8192, R, C); const int Rb = (R & ~31) + perm32(R & 31);
;         voffA[i] = (unsigned)(R * lda + C) * 2u; voffB[i] = (unsigned)(Rb * ldb + C) * 2u; }
;     const size_t kstep = (size_t)(BK * 2);
;     const size_t hA = (size_t)HALF * lda * 2, hB = (size_t)HALF * ldb * 2;
;     const unsigned ldsw = (unsigned)wid * 1024u;
;     const int aoff = lds_byte(wr * 64 + fr, fq * 8), boff = lds_byte(wc * 32 + fr, fq * 8);
;     ...
;     Unit cur, nxt; int ui = 0;
;     if (!S.next(0, cur)) return;
;     f32x4 acc[2][2][4][2];
; #pragma unroll
;     for (int a = 0; a < 2; ++a)
; #pragma unroll
;         for (int b = 0; b < 2; ++b)
; #pragma unroll
;             for (int m = 0; m < 4; ++m)
; #pragma unroll
;                 for (int n = 0; n < 2; ++n) acc[a][b][m][n] = (f32x4){0.f, 0.f, 0.f, 0.f};
;     bf16x8 At[4][2], B0[2][2], B1[2][2];
;     const char* cA = S.aptr(cur); const char* cB = S.bptr(cur);
;     PG8_STAGE(PG8_SB(0, 0), cB, voffB); PG8_STAGE(PG8_SB(0, 1), cB + hB, voffB); PG8_STAGE(PG8_SA(0, 0), cA, voffA); PG8_STAGE(PG8_SA(0, 1), cA + hA, voffA);
;     if (wr == 1) PG8_BAR;
;     PG8_WAIT_V(2); PG8_BAR;
;     PG8_STAGE(PG8_SB(1, 0), cB + kstep, voffB); PG8_STAGE(PG8_SA(1, 0), cA + kstep, voffA); PG8_STAGE(PG8_SB(1, 1), cB + hB + kstep, voffB);
;     PG8_WAIT_V(6); PG8_BAR;
.LBB0_954:
	s_or_b64 exec, exec, s[8:9]
	s_add_u32 s42, s48, 0x2e00000
	s_addc_u32 s43, s49, 0
	s_add_u32 s44, s48, 0x200000
	s_addc_u32 s45, s49, 0
	v_readlane_b32 s0, v255, 3
	s_add_u32 s12, s48, 0xa00000
	v_mov_b32_e32 v10, v254
	v_readlane_b32 s1, v255, 4
	s_addc_u32 s13, s49, 0
	s_barrier
	s_andn2_b64 vcc, exec, s[0:1]
	v_readfirstlane_b32 s9, v10
	s_cbranch_vccnz .LBB0_989
	v_lshlrev_b32_e32 v0, 4, v10
	v_add_u32_e32 v1, 0x2000, v0
	v_ashrrev_i32_e32 v2, 31, v1
	v_lshrrev_b32_e32 v2, 22, v2
	v_add_u32_e32 v2, v1, v2
	v_ashrrev_i32_e32 v8, 10, v2
	v_mul_i32_i24_e32 v2, 0x400, v8
	v_sub_u32_e32 v1, v1, v2
	v_lshrrev_b32_e32 v2, 4, v1
	v_bitop3_b32 v1, v2, v1, 32 bitop3:0x6c
	v_ashrrev_i32_e32 v2, 31, v1
	v_lshrrev_b32_e32 v2, 26, v2
	v_add_u32_e32 v2, v1, v2
	v_lshlrev_b32_e32 v3, 3, v8
	v_ashrrev_i32_e32 v9, 6, v2
	v_and_b32_e32 v3, -16, v3
	v_add_u32_e32 v3, v9, v3
	v_and_b32_e32 v4, 3, v9
	s_mov_b32 s0, 0xfffe0
	v_lshrrev_b32_e32 v5, 2, v3
	v_lshlrev_b32_e32 v6, 1, v3
	v_and_b32_e32 v2, 0xc0, v2
	v_and_or_b32 v4, v3, s0, v4
	v_and_b32_e32 v5, 4, v5
	v_and_b32_e32 v6, 24, v6
	v_sub_u32_e32 v1, v1, v2
	v_mov_b32_e32 v2, 1
	v_or3_b32 v4, v4, v5, v6
	v_lshlrev_b32_e32 v5, 5, v8
	v_ashrrev_i16_sdwa v1, v2, sext(v1) dst_sel:DWORD dst_unused:UNUSED_PAD src0_sel:DWORD src1_sel:BYTE_0
	v_and_b32_e32 v5, 32, v5
	v_bfe_i32 v11, v1, 0, 16
	v_add_lshl_u32 v1, v5, v11, 1
	v_and_b32_e32 v242, 63, v254
	v_lshrrev_b32_e32 v243, 6, v254
	v_lshrrev_b32_e32 v244, 3, v242
	v_lshl_add_u32 v245, v243, 3, v244
	v_and_b32_e32 v246, 1, v243
	v_bfe_u32 v247, v242, 4, 2
	v_lshl_add_u32 v247, v246, 2, v247
	v_and_b32_e32 v237, 7, v242
	v_xor_b32_e32 v247, v237, v247
	v_lshlrev_b32_e32 v247, 4, v247
	v_lshl_add_u32 v236, v245, 12, v247
	v_add_u32_e32 v237, 0x40000, v236
	v_lshrrev_b32_e32 v245, 5, v242
	v_lshlrev_b32_e32 v245, 3, v245
	v_lshl_add_u32 v245, v246, 4, v245
	v_bfe_u32 v246, v243, 1, 1
	v_lshl_add_u32 v245, v246, 2, v245
	v_and_b32_e32 v246, 3, v244
	v_add_u32_e32 v245, v245, v246
	v_lshrrev_b32_e32 v246, 2, v243
	v_lshl_add_u32 v245, v246, 5, v245
	v_lshl_add_u32 v238, v245, 12, v247
	v_add_u32_e32 v239, 0x40000, v238
	v_and_b32_e32 v242, 15, v254
	v_bfe_u32 v244, v254, 4, 2
	v_bfe_u32 v245, v254, 1, 3
	v_xor_b32_e32 v244, v244, v245
	v_lshlrev_b32_e32 v244, 4, v244
	v_lshl_add_u32 v244, v242, 7, v244
	v_lshrrev_b32_e32 v245, 8, v254
	v_lshl_add_u32 v240, v245, 13, v244
	v_and_b32_e32 v245, 3, v243
	v_lshl_add_u32 v241, v245, 13, v244
	v_and_b32_e32 v242, 63, v254
	v_lshrrev_b32_e32 v243, 6, v254
	v_lshrrev_b32_e32 v244, 3, v242
	v_and_b32_e32 v246, 1, v243
	v_bfe_u32 v247, v242, 4, 2
	v_lshl_add_u32 v247, v246, 2, v247
	v_and_b32_e32 v245, 7, v242
	v_xor_b32_e32 v247, v245, v247
	v_lshlrev_b32_e32 v247, 4, v247
	v_lshlrev_b32_e32 v245, 5, v246
	v_lshl_add_u32 v245, v244, 2, v245
	v_bfe_u32 v246, v243, 1, 2
	v_add_u32_e32 v245, v245, v246
	v_lshl_add_u32 v238, v245, 12, v247
	v_add_u32_e32 v239, 0x40000, v238
	v_mov_b32_e32 v128, v239
	v_mov_b32_e32 v130, v237
	v_bfe_i32 v1, v10, 27, 1
	v_lshrrev_b32_e32 v1, 22, v1
	v_add_u32_e32 v1, v0, v1
	v_and_b32_e32 v1, 0xfffffc00, v1
	v_sub_u32_e32 v0, v0, v1
	v_lshrrev_b32_e32 v1, 4, v0
	v_ashrrev_i32_e32 v3, 31, v10
	v_bitop3_b32 v0, v1, v0, 32 bitop3:0x6c
	v_lshrrev_b32_e32 v3, 26, v3
	v_ashrrev_i32_e32 v1, 31, v0
	v_add_u32_e32 v3, v10, v3
	v_lshrrev_b32_e32 v1, 26, v1
	v_ashrrev_i32_e32 v13, 6, v3
	v_add_u32_e32 v1, v0, v1
	v_lshlrev_b32_e32 v3, 3, v13
	v_ashrrev_i32_e32 v12, 6, v1
	v_and_b32_e32 v3, -16, v3
	v_add_u32_e32 v3, v12, v3
	v_and_b32_e32 v4, 3, v12
	s_ashr_i32 s4, s33, 31
	v_and_or_b32 v4, v3, s0, v4
	s_lshr_b32 s0, s4, 29
	s_add_i32 s0, s33, s0
	s_ashr_i32 s18, s9, 6
	s_ashr_i32 s1, s0, 3
	s_and_b32 s0, s0, -8
	s_ashr_i32 s17, s9, 8
	s_lshl_b32 s2, s18, 10
	s_sub_i32 s0, s33, s0
	s_cmp_lt_i32 s0, 0
	s_movk_i32 s5, 0x141
	s_cselect_b32 s6, s5, 0x140
	s_mul_i32 s0, s6, s0
	s_add_i32 s0, s0, s1
	s_mul_hi_i32 s1, s0, 0x66666667
	s_lshr_b32 s6, s1, 31
	s_ashr_i32 s1, s1, 6
	s_add_i32 s1, s1, s6
	s_lshl_b32 s6, s1, 3
	s_mulk_i32 s1, 0xa0
	s_sub_i32 s0, s0, s1
	s_sext_i32_i16 s1, s0
	s_bfe_u32 s1, s1, 0x3001c
	s_add_i32 s1, s0, s1
	s_sext_i32_i16 s7, s1
	s_and_b32 s1, s1, 0xfff8
	s_sub_i32 s0, s0, s1
	s_sext_i32_i16 s0, s0
	v_lshrrev_b32_e32 v5, 2, v3
	v_lshlrev_b32_e32 v6, 1, v3
	v_and_b32_e32 v1, 0xc0, v1
	s_lshr_b32 s8, s7, 3
	s_add_i32 s10, s6, s0
	v_and_b32_e32 v5, 4, v5
	v_and_b32_e32 v6, 24, v6
	v_sub_u32_e32 v0, v0, v1
	s_ashr_i32 s11, s10, 31
	s_bfe_i64 s[0:1], s[8:9], 0x100000
	v_or3_b32 v4, v4, v5, v6
	v_lshlrev_b32_e32 v5, 5, v13
	v_ashrrev_i16_sdwa v0, v2, sext(v0) dst_sel:DWORD dst_unused:UNUSED_PAD src0_sel:DWORD src1_sel:BYTE_0
	s_lshl_b64 s[6:7], s[10:11], 20
	s_lshl_b64 s[0:1], s[0:1], 20
	v_and_b32_e32 v5, 32, v5
	v_bfe_i32 v14, v0, 0, 16
	s_add_u32 s66, s12, s0
	v_add_lshl_u32 v0, v5, v14, 1
	s_addc_u32 s67, s13, s1
	s_add_i32 s1, s2, 0
	v_mov_b32_e32 v132, v238
	s_add_i32 m0, s1, 0x10000
	v_mov_b32_e32 v134, v236
	global_load_lds_dwordx4 v132, s[66:67]
	s_add_i32 m0, s1, 0x12000
	s_add_u32 s14, s66, 0x80000
	global_load_lds_dwordx4 v128, s[66:67]
	s_addc_u32 s15, s67, 0
	s_add_i32 m0, s1, 0x14000
	v_mov_b32_e32 v137, 0
	global_load_lds_dwordx4 v132, s[14:15]
	s_add_i32 m0, s1, 0x16000
	s_add_u32 s68, s42, s6
	s_addc_u32 s69, s43, s7
	s_add_i32 s6, s1, 0x2000
	global_load_lds_dwordx4 v128, s[14:15]
	s_mov_b32 m0, s1
	s_add_u32 s24, s68, 0x80000
	global_load_lds_dwordx4 v134, s[68:69]
	s_mov_b32 m0, s6
	s_addc_u32 s25, s69, 0
	s_add_i32 s7, s1, 0x4000
	global_load_lds_dwordx4 v130, s[68:69]
	s_mov_b32 m0, s7
	s_add_i32 s14, s1, 0x6000
	global_load_lds_dwordx4 v134, s[24:25]
	s_mov_b32 m0, s14
	v_mov_b32_e32 v133, v137
	global_load_lds_dwordx4 v130, s[24:25]
	v_mov_b32_e32 v129, v137
	v_mov_b32_e32 v135, v137
	v_mov_b32_e32 v131, v137
	s_cmp_eq_u32 s17, 1
	s_mov_b32 s19, 0
	v_lshl_add_u64 v[6:7], s[66:67], 0, v[132:133]
	v_lshl_add_u64 v[4:5], s[66:67], 0, v[128:129]
	v_lshl_add_u64 v[0:1], s[68:69], 0, v[134:135]
	s_cselect_b64 s[46:47], -1, 0
	s_cmp_lg_u32 s17, 1
	v_lshl_add_u64 v[2:3], s[68:69], 0, v[130:131]
	s_cbranch_scc1 .LBB0_957
	s_barrier

; #define PG8_STAGE(bufoff, gbase, voff) do { _Pragma("unroll") for (int _i = 0; _i < 2; ++_i) \
;         __builtin_amdgcn_global_load_lds((const unsigned*)((const char*)(gbase) + (voff)[_i]), (LAS unsigned*)(lds + (bufoff) + ldsw + _i * 8192), 16, 0, 0); } while (0)
; #define PG8_LDA(dst, b, h) do { _Pragma("unroll") for (int m = 0; m < 4; ++m) _Pragma("unroll") for (int k = 0; k < 2; ++k) dst[m][k] = *(const LAS bf16x8*)(lds + PG8_SA(b, h) + aoff + m * 2048 + k * 1024); } while (0)
; #define PG8_LDB(dst, b, h) do { _Pragma("unroll") for (int n = 0; n < 2; ++n) _Pragma("unroll") for (int k = 0; k < 2; ++k) dst[n][k] = *(const LAS bf16x8*)(lds + PG8_SB(b, h) + boff + n * 2048 + k * 1024); } while (0)
; #define PG8_WAIT_V(n) asm volatile("s_waitcnt vmcnt(" #n ")" ::: "memory")
; #define PG8_BAR __builtin_amdgcn_s_barrier()
; template <class Epi, class Sched>
; __device__ __forceinline__ void gemm_phase(LAS unsigned char* lds, const int K, const int lda, const int ldb, const Sched& S, const Epi& E) {
;     ...
;         for (int t = 0; t < nt; t += 2) {
;             const bool last = (t == nt - 2);
;             const char* a1 = cA + (size_t)(t + 1) * kstep;
;             const char* a2 = last ? nA : cA + (size_t)(t + 2) * kstep; const char* b2 = last ? nB : cB + (size_t)(t + 2) * kstep;
;             const char* a3 = a2 + kstep; const char* b3 = b2 + kstep;
;             PG8_LDB(B0, 0, 0); PG8_LDB(B1, 0, 1); PG8_SCHED; PG8_LDA(At, 0, 0); PG8_STAGE(PG8_SA(1, 1), a1 + hA, voffA);
;             PG8_WAIT_V(8); PG8_WAIT_L(0); PG8_BAR; PG8_MMA(0, 0, At, B0); PG8_MMA(0, 1, At, B1); PG8_BAR; PG8_SCHED;
;             PG8_LDA(At, 0, 1); PG8_STAGE(PG8_SB(0, 0), b2, voffB); PG8_STAGE(PG8_SB(0, 1), b2 + hB, voffB); PG8_STAGE(PG8_SA(0, 0), a2, voffA);
;             PG8_WAIT_V(8); PG8_WAIT_L(0); PG8_BAR; PG8_MMA(1, 0, At, B0); PG8_MMA(1, 1, At, B1); PG8_BAR; PG8_SCHED;
;             PG8_LDB(B0, 1, 0); PG8_LDB(B1, 1, 1); PG8_SCHED; PG8_LDA(At, 1, 0); PG8_STAGE(PG8_SA(0, 1), a2 + hA, voffA);
;             PG8_WAIT_V(8); PG8_WAIT_L(0); PG8_BAR; PG8_MMA(0, 0, At, B0); PG8_MMA(0, 1, At, B1); PG8_BAR; PG8_SCHED;
;             PG8_LDA(At, 1, 1); PG8_STAGE(PG8_SB(1, 0), b3, voffB); PG8_STAGE(PG8_SB(1, 1), b3 + hB, voffB); PG8_STAGE(PG8_SA(1, 0), a3, voffA);
;             PG8_WAIT_V(8); PG8_WAIT_L(0); PG8_BAR; PG8_MMA(1, 0, At, B0); PG8_MMA(1, 1, At, B1); PG8_BAR; PG8_SCHED;
;         }
.LBB0_963:
	ds_read_b128 v[174:177], v188
	ds_read_b128 v[178:181], v147
	ds_read_b128 v[190:193], v188 offset:2048
	ds_read_b128 v[194:197], v147 offset:2048
	ds_read_b128 v[198:201], v189
	ds_read_b128 v[202:205], v149
	ds_read_b128 v[206:209], v189 offset:2048
	ds_read_b128 v[210:213], v149 offset:2048
	s_add_u32 s61, s66, 0xfff80080
	s_addc_u32 s68, s67, -1
	s_cmp_eq_u32 s59, 28
	s_cselect_b32 s71, s11, s68
	s_cselect_b32 s70, s18, s61
	s_cselect_b32 s69, s39, s57
	s_cselect_b32 s68, s41, s55
	v_lshl_add_u64 v[182:183], s[66:67], 0, v[140:141]
	s_add_i32 m0, s1, 0xc000
	ds_read_b128 v[214:217], v163
	ds_read_b128 v[218:221], v145
	ds_read_b128 v[222:225], v163 offset:2048
	ds_read_b128 v[226:229], v145 offset:2048
	ds_read_b128 v[230:233], v163 offset:4096
	ds_read_b128 v[236:239], v145 offset:4096
	ds_read_b128 v[240:243], v163 offset:6144
	ds_read_b128 v[244:247], v145 offset:6144
	global_load_lds_dwordx4 v[182:183], off
	v_lshl_add_u64 v[182:183], s[66:67], 0, v[138:139]
	s_add_i32 m0, s1, 0xe000
	s_nop 0
	global_load_lds_dwordx4 v[182:183], off
	s_waitcnt vmcnt(8)
	s_waitcnt lgkmcnt(0)
	s_barrier
	s_setprio 1
	s_waitcnt lgkmcnt(0)
	v_mfma_f32_16x16x32_bf16 v[124:127], v[214:217], v[174:177], v[124:127]
	v_mfma_f32_16x16x32_bf16 v[120:123], v[214:217], v[190:193], v[120:123]
	v_mfma_f32_16x16x32_bf16 v[108:111], v[222:225], v[174:177], v[108:111]
	v_mfma_f32_16x16x32_bf16 v[104:107], v[222:225], v[190:193], v[104:107]
	v_mfma_f32_16x16x32_bf16 v[92:95], v[230:233], v[174:177], v[92:95]
	v_mfma_f32_16x16x32_bf16 v[88:91], v[230:233], v[190:193], v[88:91]
	v_mfma_f32_16x16x32_bf16 v[76:79], v[240:243], v[174:177], v[76:79]
	v_mfma_f32_16x16x32_bf16 v[72:75], v[240:243], v[190:193], v[72:75]
	v_mfma_f32_16x16x32_bf16 v[124:127], v[218:221], v[178:181], v[124:127]
	v_mfma_f32_16x16x32_bf16 v[120:123], v[218:221], v[194:197], v[120:123]
	v_mfma_f32_16x16x32_bf16 v[108:111], v[226:229], v[178:181], v[108:111]
	v_mfma_f32_16x16x32_bf16 v[104:107], v[226:229], v[194:197], v[104:107]
	v_mfma_f32_16x16x32_bf16 v[92:95], v[236:239], v[178:181], v[92:95]
	v_mfma_f32_16x16x32_bf16 v[88:91], v[236:239], v[194:197], v[88:91]
	v_mfma_f32_16x16x32_bf16 v[76:79], v[244:247], v[178:181], v[76:79]
	v_mfma_f32_16x16x32_bf16 v[72:75], v[244:247], v[194:197], v[72:75]
	s_setprio 0
	s_setprio 1
	v_mfma_f32_16x16x32_bf16 v[116:119], v[214:217], v[198:201], v[116:119]
	v_mfma_f32_16x16x32_bf16 v[112:115], v[214:217], v[206:209], v[112:115]
	v_mfma_f32_16x16x32_bf16 v[100:103], v[222:225], v[198:201], v[100:103]
	v_mfma_f32_16x16x32_bf16 v[96:99], v[222:225], v[206:209], v[96:99]
	v_mfma_f32_16x16x32_bf16 v[84:87], v[230:233], v[198:201], v[84:87]
	v_mfma_f32_16x16x32_bf16 v[80:83], v[230:233], v[206:209], v[80:83]
	v_mfma_f32_16x16x32_bf16 v[68:71], v[240:243], v[198:201], v[68:71]
	v_mfma_f32_16x16x32_bf16 v[64:67], v[240:243], v[206:209], v[64:67]
	v_mfma_f32_16x16x32_bf16 v[116:119], v[218:221], v[202:205], v[116:119]
	v_mfma_f32_16x16x32_bf16 v[112:115], v[218:221], v[210:213], v[112:115]
	v_mfma_f32_16x16x32_bf16 v[100:103], v[226:229], v[202:205], v[100:103]
	v_mfma_f32_16x16x32_bf16 v[96:99], v[226:229], v[210:213], v[96:99]
	v_mfma_f32_16x16x32_bf16 v[84:87], v[236:239], v[202:205], v[84:87]
	v_mfma_f32_16x16x32_bf16 v[80:83], v[236:239], v[210:213], v[80:83]
	v_mfma_f32_16x16x32_bf16 v[68:71], v[244:247], v[202:205], v[68:71]
	v_mfma_f32_16x16x32_bf16 v[64:67], v[244:247], v[210:213], v[64:67]
	s_setprio 0
	s_barrier
	s_add_i32 s61, s30, s2
	v_lshl_add_u64 v[182:183], s[68:69], 0, v[132:133]
	s_mov_b32 m0, s61
	ds_read_b128 v[214:217], v163 offset:16384
	ds_read_b128 v[218:221], v145 offset:16384
	ds_read_b128 v[222:225], v163 offset:18432
	ds_read_b128 v[226:229], v145 offset:18432
	ds_read_b128 v[230:233], v163 offset:20480
	ds_read_b128 v[236:239], v145 offset:20480
	ds_read_b128 v[240:243], v163 offset:22528
	ds_read_b128 v[244:247], v145 offset:22528
	global_load_lds_dwordx4 v[182:183], off
	s_add_i32 m0, s61, 0x2000
	s_add_u32 s72, s68, 0x80000
	v_lshl_add_u64 v[234:235], s[68:69], 0, v[128:129]
	s_addc_u32 s73, s69, 0
	s_add_i32 s61, s31, s2
	global_load_lds_dwordx4 v[234:235], off
	v_lshl_add_u64 v[248:249], s[72:73], 0, v[132:133]
	s_mov_b32 m0, s61
	v_lshl_add_u64 v[250:251], s[70:71], 0, v[130:131]
	global_load_lds_dwordx4 v[248:249], off
	v_lshl_add_u64 v[248:249], s[72:73], 0, v[128:129]
	s_add_i32 m0, s61, 0x2000
	s_nop 0
	global_load_lds_dwordx4 v[248:249], off
	v_lshl_add_u64 v[248:249], s[70:71], 0, v[134:135]
	s_mov_b32 m0, s1
	s_nop 0
	global_load_lds_dwordx4 v[248:249], off
	s_mov_b32 m0, s6
	s_nop 0
	global_load_lds_dwordx4 v[250:251], off
	s_waitcnt vmcnt(8)
	s_waitcnt lgkmcnt(0)
	s_barrier
; #define PG8_STAGE(bufoff, gbase, voff) do { _Pragma("unroll") for (int _i = 0; _i < 2; ++_i) \
;         __builtin_amdgcn_global_load_lds((const unsigned*)((const char*)(gbase) + (voff)[_i]), (LAS unsigned*)(lds + (bufoff) + ldsw + _i * 8192), 16, 0, 0); } while (0)
; #define PG8_LDA(dst, b, h) do { _Pragma("unroll") for (int m = 0; m < 4; ++m) _Pragma("unroll") for (int k = 0; k < 2; ++k) dst[m][k] = *(const LAS bf16x8*)(lds + PG8_SA(b, h) + aoff + m * 2048 + k * 1024); } while (0)
; #define PG8_LDB(dst, b, h) do { _Pragma("unroll") for (int n = 0; n < 2; ++n) _Pragma("unroll") for (int k = 0; k < 2; ++k) dst[n][k] = *(const LAS bf16x8*)(lds + PG8_SB(b, h) + boff + n * 2048 + k * 1024); } while (0)
; #define PG8_WAIT_V(n) asm volatile("s_waitcnt vmcnt(" #n ")" ::: "memory")
; #define PG8_BAR __builtin_amdgcn_s_barrier()
; template <class Epi, class Sched>
; __device__ __forceinline__ void gemm_phase(LAS unsigned char* lds, const int K, const int lda, const int ldb, const Sched& S, const Epi& E) {
;     ...
;         for (int t = 0; t < nt; t += 2) {
;             const bool last = (t == nt - 2);
;             const char* a1 = cA + (size_t)(t + 1) * kstep;
;             const char* a2 = last ? nA : cA + (size_t)(t + 2) * kstep; const char* b2 = last ? nB : cB + (size_t)(t + 2) * kstep;
;             const char* a3 = a2 + kstep; const char* b3 = b2 + kstep;
;             PG8_LDB(B0, 0, 0); PG8_LDB(B1, 0, 1); PG8_SCHED; PG8_LDA(At, 0, 0); PG8_STAGE(PG8_SA(1, 1), a1 + hA, voffA);
;             PG8_WAIT_V(8); PG8_WAIT_L(0); PG8_BAR; PG8_MMA(0, 0, At, B0); PG8_MMA(0, 1, At, B1); PG8_BAR; PG8_SCHED;
;             PG8_LDA(At, 0, 1); PG8_STAGE(PG8_SB(0, 0), b2, voffB); PG8_STAGE(PG8_SB(0, 1), b2 + hB, voffB); PG8_STAGE(PG8_SA(0, 0), a2, voffA);
;             PG8_WAIT_V(8); PG8_WAIT_L(0); PG8_BAR; PG8_MMA(1, 0, At, B0); PG8_MMA(1, 1, At, B1); PG8_BAR; PG8_SCHED;
;             PG8_LDB(B0, 1, 0); PG8_LDB(B1, 1, 1); PG8_SCHED; PG8_LDA(At, 1, 0); PG8_STAGE(PG8_SA(0, 1), a2 + hA, voffA);
;             PG8_WAIT_V(8); PG8_WAIT_L(0); PG8_BAR; PG8_MMA(0, 0, At, B0); PG8_MMA(0, 1, At, B1); PG8_BAR; PG8_SCHED;
;             PG8_LDA(At, 1, 1); PG8_STAGE(PG8_SB(1, 0), b3, voffB); PG8_STAGE(PG8_SB(1, 1), b3 + hB, voffB); PG8_STAGE(PG8_SA(1, 0), a3, voffA);
;             PG8_WAIT_V(8); PG8_WAIT_L(0); PG8_BAR; PG8_MMA(1, 0, At, B0); PG8_MMA(1, 1, At, B1); PG8_BAR; PG8_SCHED;
;         }
	s_setprio 1
	s_waitcnt lgkmcnt(0)
	v_mfma_f32_16x16x32_bf16 v[60:63], v[214:217], v[174:177], v[60:63]
	v_mfma_f32_16x16x32_bf16 v[56:59], v[214:217], v[190:193], v[56:59]
	v_mfma_f32_16x16x32_bf16 v[44:47], v[222:225], v[174:177], v[44:47]
	v_mfma_f32_16x16x32_bf16 v[40:43], v[222:225], v[190:193], v[40:43]
	v_mfma_f32_16x16x32_bf16 v[28:31], v[230:233], v[174:177], v[28:31]
	v_mfma_f32_16x16x32_bf16 v[24:27], v[230:233], v[190:193], v[24:27]
	v_mfma_f32_16x16x32_bf16 v[12:15], v[240:243], v[174:177], v[12:15]
	v_mfma_f32_16x16x32_bf16 v[8:11], v[240:243], v[190:193], v[8:11]
	v_mfma_f32_16x16x32_bf16 v[60:63], v[218:221], v[178:181], v[60:63]
	v_mfma_f32_16x16x32_bf16 v[56:59], v[218:221], v[194:197], v[56:59]
	v_mfma_f32_16x16x32_bf16 v[44:47], v[226:229], v[178:181], v[44:47]
	v_mfma_f32_16x16x32_bf16 v[40:43], v[226:229], v[194:197], v[40:43]
	v_mfma_f32_16x16x32_bf16 v[28:31], v[236:239], v[178:181], v[28:31]
	v_mfma_f32_16x16x32_bf16 v[24:27], v[236:239], v[194:197], v[24:27]
	v_mfma_f32_16x16x32_bf16 v[12:15], v[244:247], v[178:181], v[12:15]
	v_mfma_f32_16x16x32_bf16 v[8:11], v[244:247], v[194:197], v[8:11]
	s_setprio 0
	s_setprio 1
	v_mfma_f32_16x16x32_bf16 v[52:55], v[214:217], v[198:201], v[52:55]
	v_mfma_f32_16x16x32_bf16 v[48:51], v[214:217], v[206:209], v[48:51]
	v_mfma_f32_16x16x32_bf16 v[36:39], v[222:225], v[198:201], v[36:39]
	v_mfma_f32_16x16x32_bf16 v[32:35], v[222:225], v[206:209], v[32:35]
	v_mfma_f32_16x16x32_bf16 v[20:23], v[230:233], v[198:201], v[20:23]
	v_mfma_f32_16x16x32_bf16 v[16:19], v[230:233], v[206:209], v[16:19]
	v_mfma_f32_16x16x32_bf16 v[4:7], v[240:243], v[198:201], v[4:7]
	v_mfma_f32_16x16x32_bf16 v[0:3], v[240:243], v[206:209], v[0:3]
	v_mfma_f32_16x16x32_bf16 v[52:55], v[218:221], v[202:205], v[52:55]
	v_mfma_f32_16x16x32_bf16 v[48:51], v[218:221], v[210:213], v[48:51]
	v_mfma_f32_16x16x32_bf16 v[36:39], v[226:229], v[202:205], v[36:39]
	v_mfma_f32_16x16x32_bf16 v[32:35], v[226:229], v[210:213], v[32:35]
	v_mfma_f32_16x16x32_bf16 v[20:23], v[236:239], v[202:205], v[20:23]
	v_mfma_f32_16x16x32_bf16 v[16:19], v[236:239], v[210:213], v[16:19]
	v_mfma_f32_16x16x32_bf16 v[4:7], v[244:247], v[202:205], v[4:7]
	v_mfma_f32_16x16x32_bf16 v[0:3], v[244:247], v[210:213], v[0:3]
	s_setprio 0
	s_barrier
	s_add_i32 s61, 0, 0x18000
	v_add_u32_e32 v143, s61, v161
	v_add_u32_e32 v158, s61, v151
	s_add_i32 s72, 0, 0x1c000
	ds_read_b128 v[174:177], v143
	ds_read_b128 v[178:181], v158
	ds_read_b128 v[190:193], v143 offset:2048
	ds_read_b128 v[194:197], v158 offset:2048
	v_add_u32_e32 v143, 0x19000, v161
	v_add_u32_e32 v158, 0x19000, v151
	ds_read_b128 v[198:201], v143
	ds_read_b128 v[202:205], v158
	ds_read_b128 v[206:209], v143 offset:2048
	ds_read_b128 v[210:213], v158 offset:2048
	s_add_u32 s70, s70, 0x80000
	s_addc_u32 s71, s71, 0
	s_mov_b32 m0, s7
	v_lshl_add_u64 v[252:253], s[70:71], 0, v[134:135]
	ds_read_b128 v[214:217], v163 offset:32768
	ds_read_b128 v[218:221], v145 offset:32768
	ds_read_b128 v[222:225], v163 offset:34816
	ds_read_b128 v[226:229], v145 offset:34816
	ds_read_b128 v[230:233], v163 offset:36864
	ds_read_b128 v[236:239], v145 offset:36864
	ds_read_b128 v[240:243], v163 offset:38912
	ds_read_b128 v[244:247], v145 offset:38912
	global_load_lds_dwordx4 v[252:253], off
	v_lshl_add_u64 v[252:253], s[70:71], 0, v[130:131]
	s_mov_b32 m0, s14
	s_nop 0
	global_load_lds_dwordx4 v[252:253], off
	s_waitcnt vmcnt(8)
	s_waitcnt lgkmcnt(0)
	s_barrier
	s_setprio 1
	s_waitcnt lgkmcnt(0)
	v_mfma_f32_16x16x32_bf16 v[124:127], v[214:217], v[174:177], v[124:127]
	v_mfma_f32_16x16x32_bf16 v[120:123], v[214:217], v[190:193], v[120:123]
	v_mfma_f32_16x16x32_bf16 v[108:111], v[222:225], v[174:177], v[108:111]
	v_mfma_f32_16x16x32_bf16 v[104:107], v[222:225], v[190:193], v[104:107]
	v_mfma_f32_16x16x32_bf16 v[92:95], v[230:233], v[174:177], v[92:95]
	v_mfma_f32_16x16x32_bf16 v[88:91], v[230:233], v[190:193], v[88:91]
	v_mfma_f32_16x16x32_bf16 v[76:79], v[240:243], v[174:177], v[76:79]
	v_mfma_f32_16x16x32_bf16 v[72:75], v[240:243], v[190:193], v[72:75]
	v_mfma_f32_16x16x32_bf16 v[124:127], v[218:221], v[178:181], v[124:127]
	v_mfma_f32_16x16x32_bf16 v[120:123], v[218:221], v[194:197], v[120:123]
	v_mfma_f32_16x16x32_bf16 v[108:111], v[226:229], v[178:181], v[108:111]
	v_mfma_f32_16x16x32_bf16 v[104:107], v[226:229], v[194:197], v[104:107]
	v_mfma_f32_16x16x32_bf16 v[92:95], v[236:239], v[178:181], v[92:95]
	v_mfma_f32_16x16x32_bf16 v[88:91], v[236:239], v[194:197], v[88:91]
	v_mfma_f32_16x16x32_bf16 v[76:79], v[244:247], v[178:181], v[76:79]
	v_mfma_f32_16x16x32_bf16 v[72:75], v[244:247], v[194:197], v[72:75]
	s_setprio 0
	s_setprio 1
	v_mfma_f32_16x16x32_bf16 v[116:119], v[214:217], v[198:201], v[116:119]
	v_mfma_f32_16x16x32_bf16 v[112:115], v[214:217], v[206:209], v[112:115]
	v_mfma_f32_16x16x32_bf16 v[100:103], v[222:225], v[198:201], v[100:103]
	v_mfma_f32_16x16x32_bf16 v[96:99], v[222:225], v[206:209], v[96:99]
	v_mfma_f32_16x16x32_bf16 v[84:87], v[230:233], v[198:201], v[84:87]
	v_mfma_f32_16x16x32_bf16 v[80:83], v[230:233], v[206:209], v[80:83]
	v_mfma_f32_16x16x32_bf16 v[68:71], v[240:243], v[198:201], v[68:71]
	v_mfma_f32_16x16x32_bf16 v[64:67], v[240:243], v[206:209], v[64:67]
	v_mfma_f32_16x16x32_bf16 v[116:119], v[218:221], v[202:205], v[116:119]
	v_mfma_f32_16x16x32_bf16 v[112:115], v[218:221], v[210:213], v[112:115]
	v_mfma_f32_16x16x32_bf16 v[100:103], v[226:229], v[202:205], v[100:103]
	v_mfma_f32_16x16x32_bf16 v[96:99], v[226:229], v[210:213], v[96:99]
	v_mfma_f32_16x16x32_bf16 v[84:87], v[236:239], v[202:205], v[84:87]
	v_mfma_f32_16x16x32_bf16 v[80:83], v[236:239], v[210:213], v[80:83]
	v_mfma_f32_16x16x32_bf16 v[68:71], v[244:247], v[202:205], v[68:71]
	v_mfma_f32_16x16x32_bf16 v[64:67], v[244:247], v[210:213], v[64:67]
	s_setprio 0
	s_barrier
; #define PG8_STAGE(bufoff, gbase, voff) do { _Pragma("unroll") for (int _i = 0; _i < 2; ++_i) \
;         __builtin_amdgcn_global_load_lds((const unsigned*)((const char*)(gbase) + (voff)[_i]), (LAS unsigned*)(lds + (bufoff) + ldsw + _i * 8192), 16, 0, 0); } while (0)
; #define PG8_LDA(dst, b, h) do { _Pragma("unroll") for (int m = 0; m < 4; ++m) _Pragma("unroll") for (int k = 0; k < 2; ++k) dst[m][k] = *(const LAS bf16x8*)(lds + PG8_SA(b, h) + aoff + m * 2048 + k * 1024); } while (0)
; #define PG8_LDB(dst, b, h) do { _Pragma("unroll") for (int n = 0; n < 2; ++n) _Pragma("unroll") for (int k = 0; k < 2; ++k) dst[n][k] = *(const LAS bf16x8*)(lds + PG8_SB(b, h) + boff + n * 2048 + k * 1024); } while (0)
; #define PG8_WAIT_V(n) asm volatile("s_waitcnt vmcnt(" #n ")" ::: "memory")
; #define PG8_BAR __builtin_amdgcn_s_barrier()
; template <class Epi, class Sched>
; __device__ __forceinline__ void gemm_phase(LAS unsigned char* lds, const int K, const int lda, const int ldb, const Sched& S, const Epi& E) {
;     ...
;         for (int t = 0; t < nt; t += 2) {
;             const bool last = (t == nt - 2);
;             const char* a1 = cA + (size_t)(t + 1) * kstep;
;             const char* a2 = last ? nA : cA + (size_t)(t + 2) * kstep; const char* b2 = last ? nB : cB + (size_t)(t + 2) * kstep;
;             const char* a3 = a2 + kstep; const char* b3 = b2 + kstep;
;             PG8_LDB(B0, 0, 0); PG8_LDB(B1, 0, 1); PG8_SCHED; PG8_LDA(At, 0, 0); PG8_STAGE(PG8_SA(1, 1), a1 + hA, voffA);
;             PG8_WAIT_V(8); PG8_WAIT_L(0); PG8_BAR; PG8_MMA(0, 0, At, B0); PG8_MMA(0, 1, At, B1); PG8_BAR; PG8_SCHED;
;             PG8_LDA(At, 0, 1); PG8_STAGE(PG8_SB(0, 0), b2, voffB); PG8_STAGE(PG8_SB(0, 1), b2 + hB, voffB); PG8_STAGE(PG8_SA(0, 0), a2, voffA);
;             PG8_WAIT_V(8); PG8_WAIT_L(0); PG8_BAR; PG8_MMA(1, 0, At, B0); PG8_MMA(1, 1, At, B1); PG8_BAR; PG8_SCHED;
;             PG8_LDB(B0, 1, 0); PG8_LDB(B1, 1, 1); PG8_SCHED; PG8_LDA(At, 1, 0); PG8_STAGE(PG8_SA(0, 1), a2 + hA, voffA);
;             PG8_WAIT_V(8); PG8_WAIT_L(0); PG8_BAR; PG8_MMA(0, 0, At, B0); PG8_MMA(0, 1, At, B1); PG8_BAR; PG8_SCHED;
;             PG8_LDA(At, 1, 1); PG8_STAGE(PG8_SB(1, 0), b3, voffB); PG8_STAGE(PG8_SB(1, 1), b3 + hB, voffB); PG8_STAGE(PG8_SA(1, 0), a3, voffA);
;             PG8_WAIT_V(8); PG8_WAIT_L(0); PG8_BAR; PG8_MMA(1, 0, At, B0); PG8_MMA(1, 1, At, B1); PG8_BAR; PG8_SCHED;
;         }
	s_add_i32 s61, s61, s2
	v_lshl_add_u64 v[182:183], v[182:183], 0, s[50:51]
	s_mov_b32 m0, s61
	ds_read_b128 v[214:217], v163 offset:49152
	ds_read_b128 v[218:221], v145 offset:49152
	ds_read_b128 v[222:225], v163 offset:51200
	ds_read_b128 v[226:229], v145 offset:51200
	ds_read_b128 v[230:233], v163 offset:53248
	ds_read_b128 v[236:239], v145 offset:53248
	ds_read_b128 v[240:243], v163 offset:55296
	ds_read_b128 v[244:247], v145 offset:55296
	global_load_lds_dwordx4 v[182:183], off
	s_add_i32 m0, s61, 0x2000
	s_add_u32 s68, s68, 0x80080
	v_lshl_add_u64 v[182:183], v[234:235], 0, s[50:51]
	s_addc_u32 s69, s69, 0
	s_add_i32 s61, s72, s2
	global_load_lds_dwordx4 v[182:183], off
	v_lshl_add_u64 v[182:183], s[68:69], 0, v[132:133]
	s_mov_b32 m0, s61
	s_nop 0
	global_load_lds_dwordx4 v[182:183], off
	v_lshl_add_u64 v[182:183], s[68:69], 0, v[128:129]
	s_add_i32 m0, s61, 0x2000
	s_nop 0
	global_load_lds_dwordx4 v[182:183], off
	v_lshl_add_u64 v[182:183], v[248:249], 0, s[50:51]
	s_mov_b32 m0, s17
	s_nop 0
	global_load_lds_dwordx4 v[182:183], off
	v_lshl_add_u64 v[182:183], v[250:251], 0, s[50:51]
	s_mov_b32 m0, s21
	s_nop 0
	global_load_lds_dwordx4 v[182:183], off
	s_waitcnt vmcnt(8)
	s_waitcnt lgkmcnt(0)
	s_barrier
	s_setprio 1
	s_waitcnt lgkmcnt(0)
	v_mfma_f32_16x16x32_bf16 v[60:63], v[214:217], v[174:177], v[60:63]
	v_mfma_f32_16x16x32_bf16 v[56:59], v[214:217], v[190:193], v[56:59]
	v_mfma_f32_16x16x32_bf16 v[44:47], v[222:225], v[174:177], v[44:47]
	v_mfma_f32_16x16x32_bf16 v[40:43], v[222:225], v[190:193], v[40:43]
	v_mfma_f32_16x16x32_bf16 v[28:31], v[230:233], v[174:177], v[28:31]
	v_mfma_f32_16x16x32_bf16 v[24:27], v[230:233], v[190:193], v[24:27]
	v_mfma_f32_16x16x32_bf16 v[12:15], v[240:243], v[174:177], v[12:15]
	v_mfma_f32_16x16x32_bf16 v[8:11], v[240:243], v[190:193], v[8:11]
	v_mfma_f32_16x16x32_bf16 v[60:63], v[218:221], v[178:181], v[60:63]
	v_mfma_f32_16x16x32_bf16 v[56:59], v[218:221], v[194:197], v[56:59]
	v_mfma_f32_16x16x32_bf16 v[44:47], v[226:229], v[178:181], v[44:47]
	v_mfma_f32_16x16x32_bf16 v[40:43], v[226:229], v[194:197], v[40:43]
	v_mfma_f32_16x16x32_bf16 v[28:31], v[236:239], v[178:181], v[28:31]
	v_mfma_f32_16x16x32_bf16 v[24:27], v[236:239], v[194:197], v[24:27]
	v_mfma_f32_16x16x32_bf16 v[12:15], v[244:247], v[178:181], v[12:15]
	v_mfma_f32_16x16x32_bf16 v[8:11], v[244:247], v[194:197], v[8:11]
	s_setprio 0
	s_setprio 1
	v_mfma_f32_16x16x32_bf16 v[52:55], v[214:217], v[198:201], v[52:55]
	v_mfma_f32_16x16x32_bf16 v[48:51], v[214:217], v[206:209], v[48:51]
	v_mfma_f32_16x16x32_bf16 v[36:39], v[222:225], v[198:201], v[36:39]
	v_mfma_f32_16x16x32_bf16 v[32:35], v[222:225], v[206:209], v[32:35]
	v_mfma_f32_16x16x32_bf16 v[20:23], v[230:233], v[198:201], v[20:23]
	v_mfma_f32_16x16x32_bf16 v[16:19], v[230:233], v[206:209], v[16:19]
	v_mfma_f32_16x16x32_bf16 v[4:7], v[240:243], v[198:201], v[4:7]
	v_mfma_f32_16x16x32_bf16 v[0:3], v[240:243], v[206:209], v[0:3]
	v_mfma_f32_16x16x32_bf16 v[52:55], v[218:221], v[202:205], v[52:55]
	v_mfma_f32_16x16x32_bf16 v[48:51], v[218:221], v[210:213], v[48:51]
	v_mfma_f32_16x16x32_bf16 v[36:39], v[226:229], v[202:205], v[36:39]
	v_mfma_f32_16x16x32_bf16 v[32:35], v[226:229], v[210:213], v[32:35]
	v_mfma_f32_16x16x32_bf16 v[20:23], v[236:239], v[202:205], v[20:23]
	v_mfma_f32_16x16x32_bf16 v[16:19], v[236:239], v[210:213], v[16:19]
	v_mfma_f32_16x16x32_bf16 v[4:7], v[244:247], v[202:205], v[4:7]
	v_mfma_f32_16x16x32_bf16 v[0:3], v[244:247], v[210:213], v[0:3]
	s_setprio 0
	s_barrier
	s_add_i32 s59, s59, 2
	s_add_u32 s55, s55, 0x100
	s_addc_u32 s57, s57, 0
	s_add_u32 s66, s66, 0x100
	s_addc_u32 s67, s67, 0
	s_cmp_gt_u32 s59, 29
	s_cbranch_scc0 .LBB0_963
	s_and_b64 vcc, exec, s[52:53]
	s_cbranch_vccz .LBB0_966
	s_barrier

; #define LAS __attribute__((address_space(3)))
; __device__ __forceinline__ unsigned cvt_pk_bf16(float lo, float hi) { unsigned r; asm("v_cvt_pk_bf16_f32 %0, %1, %2" : "=v"(r) : "v"(lo), "v"(hi)); return r; }
; __device__ __forceinline__ void tstore_sub(const f32x4 (&v)[4][2], bf16_t* dst  , LAS unsigned char* x, int fr, int fq, int lane) {
; #pragma unroll
;     for (int m = 0; m < 4; ++m)
; #pragma unroll
;         for (int n = 0; n < 2; ++n)
; #pragma unroll
;             for (int j = 0; j < 4; ++j) {
;                 const int ch = 8 * fq + 4 * n + j, tok = 16 * m + fr;
;                 const unsigned b = cvt_pk_bf16(v[m][n][j], 0.f);
;                 *(LAS unsigned short*)(x + ch * 128 + ((((tok >> 3) ^ fq) << 4) | ((tok & 7) << 1))) = (unsigned short)b;
;             }
;     LDS_WAIT();
; #pragma unroll
;     for (int i = 0; i < 4; ++i) {
;         const int q = lane + 64 * i, ch = q >> 3, tc = q & 7;
;         const u32x4 o = *(const LAS u32x4*)(x + ch * 128 + ((tc ^ ((ch >> 3) & 3)) << 4));
;         *(u32x4*)(dst + (size_t)ch * T + tc * 8) = o;
;     }
;     LDS_WAIT();
; }
;     __device__ __forceinline__ void operator()(const f32x4 (&acc)[2][2][4][2], const Unit& u, int wr, int wc, int fr, int fq, LAS unsigned char* xs, int wid, int lane) const {
;     ...
; #pragma unroll
;             for (int ai = 0; ai < 2; ++ai)
; #pragma unroll
;                 for (int bj = 0; bj < 2; ++bj) {
;                     f32x4 v[4][2];
; #pragma unroll
;                     for (int m = 0; m < 4; ++m) { v[m][0] = acc[ai][bj][m][0] * rs[ai][m]; v[m][1] = acc[ai][bj][m][1] * rs[ai][m]; }
;                     if (ODD) {
;                         float* vss = (float*)(ws + OFF_VSS);
; #pragma unroll
;                         for (int m = 0; m < 4; ++m) {
;                             float s = 0.f;
; #pragma unroll
;                             for (int n = 0; n < 2; ++n) s += (v[m][n][0] * v[m][n][0] + v[m][n][1] * v[m][n][1]) + (v[m][n][2] * v[m][n][2] + v[m][n][3] * v[m][n][3]);
;                             s += __shfl_xor(s, 16); s += __shfl_xor(s, 32);
;                             if (fq == 0) vss[(size_t)(row0 + ai * 128 + m * 16 + fr) * 32 + (2 * (pn - 24) + bj) * 4 + wc] = s;
;                         }
;                     }
;                     tstore_sub(v, base + (size_t)(bj * 128 + wc * 32) * T + row0 + ai * 128, x, fr, fq, lane);
;                 }
.LBB0_984:
	v_and_b32_e32 v233, 0x1c0, v254
	v_lshlrev_b32_e32 v233, 6, v233
	v_add_u32_e32 v233, 0x20000, v233
	v_and_b32_e32 v232, 63, v254
	v_lshl_add_u32 v232, v232, 2, v233
	ds_write_b32 v232, v143
	ds_write_b32 v232, v145 offset:256
	v_bfe_u32 v232, v254, 4, 2
	v_lshl_add_u32 v233, v232, 4, v233
	ds_read_b128 v[190:193], v233
	ds_read_b128 v[194:197], v233 offset:64
	ds_read_b128 v[198:201], v233 offset:128
	ds_read_b128 v[202:205], v233 offset:192
	ds_read_b128 v[206:209], v233 offset:256
	ds_read_b128 v[210:213], v233 offset:320
	ds_read_b128 v[214:217], v233 offset:384
	ds_read_b128 v[218:221], v233 offset:448
	v_and_b32_e32 v240, 0x1c0, v254
	v_lshlrev_b32_e32 v240, 6, v240
	v_add_u32_e32 v240, 0x20000, v240
	v_and_b32_e32 v232, 15, v254
	v_bfe_u32 v239, v254, 4, 2
	v_lshrrev_b32_e32 v241, 1, v239
	v_and_b32_e32 v235, 7, v232
	v_xor_b32_e32 v241, v241, v235
	v_lshlrev_b32_e32 v241, 4, v241
	v_and_b32_e32 v235, 1, v239
	v_lshl_add_u32 v241, v235, 3, v241
	v_lshl_add_u32 v241, v232, 8, v241
	v_add_u32_e32 v241, v240, v241
	v_and_b32_e32 v232, 63, v254
	v_lshrrev_b32_e32 v242, 4, v232
	v_and_b32_e32 v235, 7, v232
	v_xor_b32_e32 v242, v242, v235
	v_lshlrev_b32_e32 v242, 4, v242
	v_lshrrev_b32_e32 v236, 3, v232
	v_lshl_add_u32 v242, v236, 7, v242
	v_add_u32_e32 v242, v240, v242
	v_xor_b32_e32 v243, 64, v242
	v_and_b32_e32 v237, 1, v236
	v_lshlrev_b32_e32 v234, 1, v236
	v_sub_u32_e32 v234, v234, v237
	v_lshrrev_b32_e32 v237, 6, v254
	v_and_b32_e32 v237, 3, v237
	v_lshl_add_u32 v234, v237, 6, v234
	v_lshlrev_b32_e32 v234, 16, v234
	v_lshl_add_u32 v234, v235, 4, v234
	s_lshl_b32 s0, s66, 1
	s_add_u32 s70, s68, s0
	s_addc_u32 s71, s69, 0
	s_waitcnt lgkmcnt(0)
	v_mul_f32_e32 v235, v124, v190
	v_mul_f32_e32 v236, v125, v191
	v_mul_f32_e32 v237, v126, v192
	v_mul_f32_e32 v238, v127, v193
	v_cvt_pk_bf16_f32 v224, v235, v236
	v_cvt_pk_bf16_f32 v225, v237, v238
	ds_write_b64 v241, v[224:225]
	v_mul_f32_e32 v235, v120, v190
	v_mul_f32_e32 v236, v121, v191
	v_mul_f32_e32 v237, v122, v192
	v_mul_f32_e32 v238, v123, v193
	v_cvt_pk_bf16_f32 v226, v235, v236
	v_cvt_pk_bf16_f32 v227, v237, v238
	ds_write_b64 v241, v[226:227] offset:128
	v_xor_b32_e32 v239, 0x20, v241
	v_mul_f32_e32 v235, v108, v194
	v_mul_f32_e32 v236, v109, v195
	v_mul_f32_e32 v237, v110, v196
	v_mul_f32_e32 v238, v111, v197
	v_cvt_pk_bf16_f32 v228, v235, v236
	v_cvt_pk_bf16_f32 v229, v237, v238
	ds_write_b64 v239, v[228:229]
	v_mul_f32_e32 v235, v104, v194
	v_mul_f32_e32 v236, v105, v195
	v_mul_f32_e32 v237, v106, v196
	v_mul_f32_e32 v238, v107, v197
	v_cvt_pk_bf16_f32 v230, v235, v236
	v_cvt_pk_bf16_f32 v231, v237, v238
	ds_write_b64 v239, v[230:231] offset:128
	v_xor_b32_e32 v239, 0x40, v241
	v_mul_f32_e32 v235, v92, v198
	v_mul_f32_e32 v236, v93, v199
	v_mul_f32_e32 v237, v94, v200
	v_mul_f32_e32 v238, v95, v201
	v_cvt_pk_bf16_f32 v224, v235, v236
	v_cvt_pk_bf16_f32 v225, v237, v238
	ds_write_b64 v239, v[224:225]
	v_mul_f32_e32 v235, v88, v198
	v_mul_f32_e32 v236, v89, v199
	v_mul_f32_e32 v237, v90, v200
	v_mul_f32_e32 v238, v91, v201
	v_cvt_pk_bf16_f32 v226, v235, v236
	v_cvt_pk_bf16_f32 v227, v237, v238
	ds_write_b64 v239, v[226:227] offset:128
	v_xor_b32_e32 v239, 0x60, v241
	v_mul_f32_e32 v235, v76, v202
	v_mul_f32_e32 v236, v77, v203
	v_mul_f32_e32 v237, v78, v204
	v_mul_f32_e32 v238, v79, v205
	v_cvt_pk_bf16_f32 v228, v235, v236
	v_cvt_pk_bf16_f32 v229, v237, v238
	ds_write_b64 v239, v[228:229]
	v_mul_f32_e32 v235, v72, v202
	v_mul_f32_e32 v236, v73, v203
	v_mul_f32_e32 v237, v74, v204
	v_mul_f32_e32 v238, v75, v205
	v_cvt_pk_bf16_f32 v230, v235, v236
	v_cvt_pk_bf16_f32 v231, v237, v238
	ds_write_b64 v239, v[230:231] offset:128
	ds_read_b128 v[176:179], v242
	ds_read_b128 v[180:183], v243 offset:1024
	ds_read_b128 v[244:247], v242 offset:2048
	ds_read_b128 v[248:251], v243 offset:3072
	s_waitcnt lgkmcnt(3)
	s_add_u32 s72, s70, 0x0
	s_addc_u32 s73, s71, 0
	global_store_dwordx4 v234, v[176:179], s[72:73]
	s_waitcnt lgkmcnt(2)
	s_add_u32 s72, s70, 0x100000
	s_addc_u32 s73, s71, 0
	global_store_dwordx4 v234, v[180:183], s[72:73]
	s_waitcnt lgkmcnt(1)
	s_add_u32 s72, s70, 0x200000
	s_addc_u32 s73, s71, 0
	global_store_dwordx4 v234, v[244:247], s[72:73]
	s_waitcnt lgkmcnt(0)
	s_add_u32 s72, s70, 0x300000
	s_addc_u32 s73, s71, 0
	global_store_dwordx4 v234, v[248:251], s[72:73]
	v_mul_f32_e32 v235, v116, v190
	v_mul_f32_e32 v236, v117, v191
	v_mul_f32_e32 v237, v118, v192
	v_mul_f32_e32 v238, v119, v193
	v_cvt_pk_bf16_f32 v224, v235, v236
	v_cvt_pk_bf16_f32 v225, v237, v238
	ds_write_b64 v241, v[224:225]
	v_mul_f32_e32 v235, v112, v190
	v_mul_f32_e32 v236, v113, v191
	v_mul_f32_e32 v237, v114, v192
	v_mul_f32_e32 v238, v115, v193
	v_cvt_pk_bf16_f32 v226, v235, v236
	v_cvt_pk_bf16_f32 v227, v237, v238
	ds_write_b64 v241, v[226:227] offset:128
	v_xor_b32_e32 v239, 0x20, v241
	v_mul_f32_e32 v235, v100, v194
	v_mul_f32_e32 v236, v101, v195
	v_mul_f32_e32 v237, v102, v196
	v_mul_f32_e32 v238, v103, v197
	v_cvt_pk_bf16_f32 v228, v235, v236
	v_cvt_pk_bf16_f32 v229, v237, v238
	ds_write_b64 v239, v[228:229]
	v_mul_f32_e32 v235, v96, v194
	v_mul_f32_e32 v236, v97, v195
	v_mul_f32_e32 v237, v98, v196
	v_mul_f32_e32 v238, v99, v197
	v_cvt_pk_bf16_f32 v230, v235, v236
	v_cvt_pk_bf16_f32 v231, v237, v238
	ds_write_b64 v239, v[230:231] offset:128
	v_xor_b32_e32 v239, 0x40, v241
	v_mul_f32_e32 v235, v84, v198
	v_mul_f32_e32 v236, v85, v199
	v_mul_f32_e32 v237, v86, v200
	v_mul_f32_e32 v238, v87, v201
	v_cvt_pk_bf16_f32 v224, v235, v236
	v_cvt_pk_bf16_f32 v225, v237, v238
	ds_write_b64 v239, v[224:225]
	v_mul_f32_e32 v235, v80, v198
	v_mul_f32_e32 v236, v81, v199
	v_mul_f32_e32 v237, v82, v200
	v_mul_f32_e32 v238, v83, v201
	v_cvt_pk_bf16_f32 v226, v235, v236
	v_cvt_pk_bf16_f32 v227, v237, v238
	ds_write_b64 v239, v[226:227] offset:128
	v_xor_b32_e32 v239, 0x60, v241
	v_mul_f32_e32 v235, v68, v202
	v_mul_f32_e32 v236, v69, v203
	v_mul_f32_e32 v237, v70, v204
	v_mul_f32_e32 v238, v71, v205
	v_cvt_pk_bf16_f32 v228, v235, v236
	v_cvt_pk_bf16_f32 v229, v237, v238
	ds_write_b64 v239, v[228:229]
	v_mul_f32_e32 v235, v64, v202
	v_mul_f32_e32 v236, v65, v203
	v_mul_f32_e32 v237, v66, v204
	v_mul_f32_e32 v238, v67, v205
	v_cvt_pk_bf16_f32 v230, v235, v236
	v_cvt_pk_bf16_f32 v231, v237, v238
	ds_write_b64 v239, v[230:231] offset:128
	ds_read_b128 v[176:179], v242
	ds_read_b128 v[180:183], v243 offset:1024
	ds_read_b128 v[244:247], v242 offset:2048
	ds_read_b128 v[248:251], v243 offset:3072
	s_waitcnt lgkmcnt(3)
; #define LAS __attribute__((address_space(3)))
; __device__ __forceinline__ unsigned cvt_pk_bf16(float lo, float hi) { unsigned r; asm("v_cvt_pk_bf16_f32 %0, %1, %2" : "=v"(r) : "v"(lo), "v"(hi)); return r; }
; __device__ __forceinline__ void tstore_sub(const f32x4 (&v)[4][2], bf16_t* dst  , LAS unsigned char* x, int fr, int fq, int lane) {
; #pragma unroll
;     for (int m = 0; m < 4; ++m)
; #pragma unroll
;         for (int n = 0; n < 2; ++n)
; #pragma unroll
;             for (int j = 0; j < 4; ++j) {
;                 const int ch = 8 * fq + 4 * n + j, tok = 16 * m + fr;
;                 const unsigned b = cvt_pk_bf16(v[m][n][j], 0.f);
;                 *(LAS unsigned short*)(x + ch * 128 + ((((tok >> 3) ^ fq) << 4) | ((tok & 7) << 1))) = (unsigned short)b;
;             }
;     LDS_WAIT();
; #pragma unroll
;     for (int i = 0; i < 4; ++i) {
;         const int q = lane + 64 * i, ch = q >> 3, tc = q & 7;
;         const u32x4 o = *(const LAS u32x4*)(x + ch * 128 + ((tc ^ ((ch >> 3) & 3)) << 4));
;         *(u32x4*)(dst + (size_t)ch * T + tc * 8) = o;
;     }
;     LDS_WAIT();
; }
;     __device__ __forceinline__ void operator()(const f32x4 (&acc)[2][2][4][2], const Unit& u, int wr, int wc, int fr, int fq, LAS unsigned char* xs, int wid, int lane) const {
;     ...
; #pragma unroll
;             for (int ai = 0; ai < 2; ++ai)
; #pragma unroll
;                 for (int bj = 0; bj < 2; ++bj) {
;                     f32x4 v[4][2];
; #pragma unroll
;                     for (int m = 0; m < 4; ++m) { v[m][0] = acc[ai][bj][m][0] * rs[ai][m]; v[m][1] = acc[ai][bj][m][1] * rs[ai][m]; }
;                     if (ODD) {
;                         float* vss = (float*)(ws + OFF_VSS);
; #pragma unroll
;                         for (int m = 0; m < 4; ++m) {
;                             float s = 0.f;
; #pragma unroll
;                             for (int n = 0; n < 2; ++n) s += (v[m][n][0] * v[m][n][0] + v[m][n][1] * v[m][n][1]) + (v[m][n][2] * v[m][n][2] + v[m][n][3] * v[m][n][3]);
;                             s += __shfl_xor(s, 16); s += __shfl_xor(s, 32);
;                             if (fq == 0) vss[(size_t)(row0 + ai * 128 + m * 16 + fr) * 32 + (2 * (pn - 24) + bj) * 4 + wc] = s;
;                         }
;                     }
;                     tstore_sub(v, base + (size_t)(bj * 128 + wc * 32) * T + row0 + ai * 128, x, fr, fq, lane);
;                 }
	s_add_u32 s72, s70, 0x20000
	s_addc_u32 s73, s71, 0
	global_store_dwordx4 v234, v[176:179], s[72:73]
	s_waitcnt lgkmcnt(2)
	s_add_u32 s72, s70, 0x120000
	s_addc_u32 s73, s71, 0
	global_store_dwordx4 v234, v[180:183], s[72:73]
	s_waitcnt lgkmcnt(1)
	s_add_u32 s72, s70, 0x220000
	s_addc_u32 s73, s71, 0
	global_store_dwordx4 v234, v[244:247], s[72:73]
	s_waitcnt lgkmcnt(0)
	s_add_u32 s72, s70, 0x320000
	s_addc_u32 s73, s71, 0
	global_store_dwordx4 v234, v[248:251], s[72:73]
	v_mul_f32_e32 v235, v60, v206
	v_mul_f32_e32 v236, v61, v207
	v_mul_f32_e32 v237, v62, v208
	v_mul_f32_e32 v238, v63, v209
	v_cvt_pk_bf16_f32 v224, v235, v236
	v_cvt_pk_bf16_f32 v225, v237, v238
	ds_write_b64 v241, v[224:225]
	v_mul_f32_e32 v235, v56, v206
	v_mul_f32_e32 v236, v57, v207
	v_mul_f32_e32 v237, v58, v208
	v_mul_f32_e32 v238, v59, v209
	v_cvt_pk_bf16_f32 v226, v235, v236
	v_cvt_pk_bf16_f32 v227, v237, v238
	ds_write_b64 v241, v[226:227] offset:128
	v_xor_b32_e32 v239, 0x20, v241
	v_mul_f32_e32 v235, v44, v210
	v_mul_f32_e32 v236, v45, v211
	v_mul_f32_e32 v237, v46, v212
	v_mul_f32_e32 v238, v47, v213
	v_cvt_pk_bf16_f32 v228, v235, v236
	v_cvt_pk_bf16_f32 v229, v237, v238
	ds_write_b64 v239, v[228:229]
	v_mul_f32_e32 v235, v40, v210
	v_mul_f32_e32 v236, v41, v211
	v_mul_f32_e32 v237, v42, v212
	v_mul_f32_e32 v238, v43, v213
	v_cvt_pk_bf16_f32 v230, v235, v236
	v_cvt_pk_bf16_f32 v231, v237, v238
	ds_write_b64 v239, v[230:231] offset:128
	v_xor_b32_e32 v239, 0x40, v241
	v_mul_f32_e32 v235, v28, v214
	v_mul_f32_e32 v236, v29, v215
	v_mul_f32_e32 v237, v30, v216
	v_mul_f32_e32 v238, v31, v217
	v_cvt_pk_bf16_f32 v224, v235, v236
	v_cvt_pk_bf16_f32 v225, v237, v238
	ds_write_b64 v239, v[224:225]
	v_mul_f32_e32 v235, v24, v214
	v_mul_f32_e32 v236, v25, v215
	v_mul_f32_e32 v237, v26, v216
	v_mul_f32_e32 v238, v27, v217
	v_cvt_pk_bf16_f32 v226, v235, v236
	v_cvt_pk_bf16_f32 v227, v237, v238
	ds_write_b64 v239, v[226:227] offset:128
	v_xor_b32_e32 v239, 0x60, v241
	v_mul_f32_e32 v235, v12, v218
	v_mul_f32_e32 v236, v13, v219
	v_mul_f32_e32 v237, v14, v220
	v_mul_f32_e32 v238, v15, v221
	v_cvt_pk_bf16_f32 v228, v235, v236
	v_cvt_pk_bf16_f32 v229, v237, v238
	ds_write_b64 v239, v[228:229]
	v_mul_f32_e32 v235, v8, v218
	v_mul_f32_e32 v236, v9, v219
	v_mul_f32_e32 v237, v10, v220
	v_mul_f32_e32 v238, v11, v221
	v_cvt_pk_bf16_f32 v230, v235, v236
	v_cvt_pk_bf16_f32 v231, v237, v238
	ds_write_b64 v239, v[230:231] offset:128
	ds_read_b128 v[176:179], v242
	ds_read_b128 v[180:183], v243 offset:1024
	ds_read_b128 v[244:247], v242 offset:2048
	ds_read_b128 v[248:251], v243 offset:3072
	s_waitcnt lgkmcnt(3)
	s_add_u32 s72, s70, 0x100
	s_addc_u32 s73, s71, 0
	global_store_dwordx4 v234, v[176:179], s[72:73]
	s_waitcnt lgkmcnt(2)
	s_add_u32 s72, s70, 0x100100
	s_addc_u32 s73, s71, 0
	global_store_dwordx4 v234, v[180:183], s[72:73]
	s_waitcnt lgkmcnt(1)
	s_add_u32 s72, s70, 0x200100
	s_addc_u32 s73, s71, 0
	global_store_dwordx4 v234, v[244:247], s[72:73]
	s_waitcnt lgkmcnt(0)
	s_add_u32 s72, s70, 0x300100
	s_addc_u32 s73, s71, 0
	global_store_dwordx4 v234, v[248:251], s[72:73]
	v_mul_f32_e32 v235, v52, v206
	v_mul_f32_e32 v236, v53, v207
	v_mul_f32_e32 v237, v54, v208
	v_mul_f32_e32 v238, v55, v209
	v_cvt_pk_bf16_f32 v224, v235, v236
	v_cvt_pk_bf16_f32 v225, v237, v238
	ds_write_b64 v241, v[224:225]
	v_mul_f32_e32 v235, v48, v206
	v_mul_f32_e32 v236, v49, v207
	v_mul_f32_e32 v237, v50, v208
	v_mul_f32_e32 v238, v51, v209
	v_cvt_pk_bf16_f32 v226, v235, v236
	v_cvt_pk_bf16_f32 v227, v237, v238
	ds_write_b64 v241, v[226:227] offset:128
	v_xor_b32_e32 v239, 0x20, v241
	v_mul_f32_e32 v235, v36, v210
	v_mul_f32_e32 v236, v37, v211
	v_mul_f32_e32 v237, v38, v212
	v_mul_f32_e32 v238, v39, v213
	v_cvt_pk_bf16_f32 v228, v235, v236
	v_cvt_pk_bf16_f32 v229, v237, v238
	ds_write_b64 v239, v[228:229]
	v_mul_f32_e32 v235, v32, v210
	v_mul_f32_e32 v236, v33, v211
	v_mul_f32_e32 v237, v34, v212
	v_mul_f32_e32 v238, v35, v213
	v_cvt_pk_bf16_f32 v230, v235, v236
	v_cvt_pk_bf16_f32 v231, v237, v238
	ds_write_b64 v239, v[230:231] offset:128
	v_xor_b32_e32 v239, 0x40, v241
	v_mul_f32_e32 v235, v20, v214
	v_mul_f32_e32 v236, v21, v215
	v_mul_f32_e32 v237, v22, v216
	v_mul_f32_e32 v238, v23, v217
	v_cvt_pk_bf16_f32 v224, v235, v236
	v_cvt_pk_bf16_f32 v225, v237, v238
	ds_write_b64 v239, v[224:225]
	v_mul_f32_e32 v235, v16, v214
	v_mul_f32_e32 v236, v17, v215
	v_mul_f32_e32 v237, v18, v216
	v_mul_f32_e32 v238, v19, v217
	v_cvt_pk_bf16_f32 v226, v235, v236
	v_cvt_pk_bf16_f32 v227, v237, v238
	ds_write_b64 v239, v[226:227] offset:128
	v_xor_b32_e32 v239, 0x60, v241
	v_mul_f32_e32 v235, v4, v218
	v_mul_f32_e32 v236, v5, v219
	v_mul_f32_e32 v237, v6, v220
	v_mul_f32_e32 v238, v7, v221
	v_cvt_pk_bf16_f32 v228, v235, v236
	v_cvt_pk_bf16_f32 v229, v237, v238
	ds_write_b64 v239, v[228:229]
	v_mul_f32_e32 v235, v0, v218
	v_mul_f32_e32 v236, v1, v219
	v_mul_f32_e32 v237, v2, v220
	v_mul_f32_e32 v238, v3, v221
	v_cvt_pk_bf16_f32 v230, v235, v236
	v_cvt_pk_bf16_f32 v231, v237, v238
	ds_write_b64 v239, v[230:231] offset:128
	ds_read_b128 v[176:179], v242
	ds_read_b128 v[180:183], v243 offset:1024
	ds_read_b128 v[244:247], v242 offset:2048
	ds_read_b128 v[248:251], v243 offset:3072
	s_waitcnt lgkmcnt(3)
	s_add_u32 s72, s70, 0x20100
	s_addc_u32 s73, s71, 0
	global_store_dwordx4 v234, v[176:179], s[72:73]
	s_waitcnt lgkmcnt(2)
	s_add_u32 s72, s70, 0x120100
	s_addc_u32 s73, s71, 0
	global_store_dwordx4 v234, v[180:183], s[72:73]
	s_waitcnt lgkmcnt(1)
	s_add_u32 s72, s70, 0x220100
	s_addc_u32 s73, s71, 0
	global_store_dwordx4 v234, v[244:247], s[72:73]
	s_waitcnt lgkmcnt(0)
	s_add_u32 s72, s70, 0x320100
	s_addc_u32 s73, s71, 0
	global_store_dwordx4 v234, v[248:251], s[72:73]
	s_branch .LBB0_970
; __device__ __forceinline__ unsigned cvt_pk_bf16(float lo, float hi) { unsigned r; asm("v_cvt_pk_bf16_f32 %0, %1, %2" : "=v"(r) : "v"(lo), "v"(hi)); return r; }
;     __device__ __forceinline__ void operator()(const f32x4 (&acc)[2][2][4][2], const Unit& u, int wr, int wc, int fr, int fq, LAS unsigned char* xs, int wid, int lane) const {
;     ...
;         for (int ai = 0; ai < 2; ++ai) {
;             const f32x4* pp = (const f32x4*)(rss + (size_t)(row0 + ai * 128 + lane) * 8);
;             const f32x4 v0 = pp[0], v1 = pp[1];
;             const float s = ((v0[0] + v0[1]) + (v0[2] + v0[3])) + ((v1[0] + v1[1]) + (v1[2] + v1[3]));
;             const float r = rsqrtf(s * (1.f / D) + EPS);
; #pragma unroll
;             for (int m = 0; m < 4; ++m) rs[ai][m] = __shfl(r, 16 * m + fr);
;         }
;     ...
;         if (mode == 0) {
; #pragma unroll
;             for (int ai = 0; ai < 2; ++ai)
; #pragma unroll
;                 for (int m = 0; m < 4; ++m) {
;                     const float r = rs[ai][m];
;                     bf16_t* rowp = base + (size_t)(row0 + ai * 128 + m * 16 + fr) * ldc + wc * 32 + 8 * fq;
; #pragma unroll
;                     for (int bj = 0; bj < 2; ++bj) { const f32x4 v0 = acc[ai][bj][m][0] * r, v1 = acc[ai][bj][m][1] * r;
;                         u32x4 w; w.x = cvt_pk_bf16(v0[0], v0[1]); w.y = cvt_pk_bf16(v0[2], v0[3]); w.z = cvt_pk_bf16(v1[0], v1[1]); w.w = cvt_pk_bf16(v1[2], v1[3]);
;                         *(u32x4*)(rowp + bj * 128) = w; }
;                     __builtin_amdgcn_sched_barrier(0);
;                 }
.LBB0_985:
	v_and_b32_e32 v233, 0x1c0, v254
	v_lshlrev_b32_e32 v233, 6, v233
	v_add_u32_e32 v233, 0x20000, v233
	v_and_b32_e32 v232, 63, v254
	v_lshl_add_u32 v232, v232, 2, v233
	ds_write_b32 v232, v143
	ds_write_b32 v232, v145 offset:256
	v_bfe_u32 v232, v254, 4, 2
	v_lshl_add_u32 v233, v232, 4, v233
	ds_read_b128 v[190:193], v233
	ds_read_b128 v[194:197], v233 offset:64
	ds_read_b128 v[198:201], v233 offset:128
	ds_read_b128 v[202:205], v233 offset:192
	ds_read_b128 v[206:209], v233 offset:256
	ds_read_b128 v[210:213], v233 offset:320
	ds_read_b128 v[214:217], v233 offset:384
	ds_read_b128 v[218:221], v233 offset:448
	v_bfe_u32 v234, v254, 4, 2
	v_lshlrev_b32_e32 v234, 2, v234
	v_mul_lo_u32 v234, v234, s10
	v_and_b32_e32 v232, 15, v254
	v_lshl_add_u32 v234, v232, 2, v234
	v_lshrrev_b32_e32 v232, 6, v254
	v_and_b32_e32 v232, 3, v232
	v_lshl_add_u32 v234, v232, 6, v234
	v_lshlrev_b32_e32 v234, 1, v234
	s_mul_i32 s0, s66, s10
	s_lshl_b32 s0, s0, 1
	s_add_u32 s70, s68, s0
	s_addc_u32 s71, s69, 0
	s_lshl_b32 s18, s10, 1
	s_waitcnt lgkmcnt(0)
	v_mul_f32_e32 v235, v124, v190
	v_mul_f32_e32 v236, v120, v190
	v_mul_f32_e32 v237, v116, v190
	v_mul_f32_e32 v238, v112, v190
	v_cvt_pk_bf16_f32 v224, v235, v236
	v_cvt_pk_bf16_f32 v225, v237, v238
	global_store_dwordx2 v234, v[224:225], s[70:71]
	v_mul_f32_e32 v235, v125, v191
	v_mul_f32_e32 v236, v121, v191
	v_mul_f32_e32 v237, v117, v191
	v_mul_f32_e32 v238, v113, v191
	v_cvt_pk_bf16_f32 v226, v235, v236
	v_cvt_pk_bf16_f32 v227, v237, v238
	s_mul_i32 s0, s18, 0x1
	s_add_u32 s74, s70, s0
	s_addc_u32 s75, s71, 0
	global_store_dwordx2 v234, v[226:227], s[74:75]
	v_mul_f32_e32 v235, v126, v192
	v_mul_f32_e32 v236, v122, v192
	v_mul_f32_e32 v237, v118, v192
	v_mul_f32_e32 v238, v114, v192
	v_cvt_pk_bf16_f32 v228, v235, v236
	v_cvt_pk_bf16_f32 v229, v237, v238
	s_mul_i32 s0, s18, 0x2
	s_add_u32 s72, s70, s0
	s_addc_u32 s73, s71, 0
	global_store_dwordx2 v234, v[228:229], s[72:73]
	v_mul_f32_e32 v235, v127, v193
	v_mul_f32_e32 v236, v123, v193
	v_mul_f32_e32 v237, v119, v193
	v_mul_f32_e32 v238, v115, v193
	v_cvt_pk_bf16_f32 v230, v235, v236
	v_cvt_pk_bf16_f32 v231, v237, v238
	s_mul_i32 s0, s18, 0x3
	s_add_u32 s74, s70, s0
	s_addc_u32 s75, s71, 0
	global_store_dwordx2 v234, v[230:231], s[74:75]
	v_mul_f32_e32 v235, v108, v194
	v_mul_f32_e32 v236, v104, v194
	v_mul_f32_e32 v237, v100, v194
	v_mul_f32_e32 v238, v96, v194
	v_cvt_pk_bf16_f32 v224, v235, v236
	v_cvt_pk_bf16_f32 v225, v237, v238
	s_mul_i32 s0, s18, 0x10
	s_add_u32 s72, s70, s0
	s_addc_u32 s73, s71, 0
	global_store_dwordx2 v234, v[224:225], s[72:73]
	v_mul_f32_e32 v235, v109, v195
	v_mul_f32_e32 v236, v105, v195
	v_mul_f32_e32 v237, v101, v195
	v_mul_f32_e32 v238, v97, v195
	v_cvt_pk_bf16_f32 v226, v235, v236
	v_cvt_pk_bf16_f32 v227, v237, v238
	s_mul_i32 s0, s18, 0x11
	s_add_u32 s74, s70, s0
	s_addc_u32 s75, s71, 0
	global_store_dwordx2 v234, v[226:227], s[74:75]
	v_mul_f32_e32 v235, v110, v196
	v_mul_f32_e32 v236, v106, v196
	v_mul_f32_e32 v237, v102, v196
	v_mul_f32_e32 v238, v98, v196
	v_cvt_pk_bf16_f32 v228, v235, v236
	v_cvt_pk_bf16_f32 v229, v237, v238
	s_mul_i32 s0, s18, 0x12
	s_add_u32 s72, s70, s0
	s_addc_u32 s73, s71, 0
	global_store_dwordx2 v234, v[228:229], s[72:73]
	v_mul_f32_e32 v235, v111, v197
	v_mul_f32_e32 v236, v107, v197
	v_mul_f32_e32 v237, v103, v197
	v_mul_f32_e32 v238, v99, v197
	v_cvt_pk_bf16_f32 v230, v235, v236
	v_cvt_pk_bf16_f32 v231, v237, v238
	s_mul_i32 s0, s18, 0x13
	s_add_u32 s74, s70, s0
	s_addc_u32 s75, s71, 0
	global_store_dwordx2 v234, v[230:231], s[74:75]
	v_mul_f32_e32 v235, v92, v198
	v_mul_f32_e32 v236, v88, v198
	v_mul_f32_e32 v237, v84, v198
	v_mul_f32_e32 v238, v80, v198
	v_cvt_pk_bf16_f32 v224, v235, v236
	v_cvt_pk_bf16_f32 v225, v237, v238
	s_mul_i32 s0, s18, 0x20
	s_add_u32 s72, s70, s0
	s_addc_u32 s73, s71, 0
	global_store_dwordx2 v234, v[224:225], s[72:73]
	v_mul_f32_e32 v235, v93, v199
	v_mul_f32_e32 v236, v89, v199
	v_mul_f32_e32 v237, v85, v199
	v_mul_f32_e32 v238, v81, v199
	v_cvt_pk_bf16_f32 v226, v235, v236
	v_cvt_pk_bf16_f32 v227, v237, v238
	s_mul_i32 s0, s18, 0x21
	s_add_u32 s74, s70, s0
	s_addc_u32 s75, s71, 0
	global_store_dwordx2 v234, v[226:227], s[74:75]
	v_mul_f32_e32 v235, v94, v200
	v_mul_f32_e32 v236, v90, v200
	v_mul_f32_e32 v237, v86, v200
	v_mul_f32_e32 v238, v82, v200
	v_cvt_pk_bf16_f32 v228, v235, v236
	v_cvt_pk_bf16_f32 v229, v237, v238
	s_mul_i32 s0, s18, 0x22
	s_add_u32 s72, s70, s0
	s_addc_u32 s73, s71, 0
	global_store_dwordx2 v234, v[228:229], s[72:73]
	v_mul_f32_e32 v235, v95, v201
	v_mul_f32_e32 v236, v91, v201
	v_mul_f32_e32 v237, v87, v201
	v_mul_f32_e32 v238, v83, v201
	v_cvt_pk_bf16_f32 v230, v235, v236
	v_cvt_pk_bf16_f32 v231, v237, v238
	s_mul_i32 s0, s18, 0x23
	s_add_u32 s74, s70, s0
	s_addc_u32 s75, s71, 0
	global_store_dwordx2 v234, v[230:231], s[74:75]
	v_mul_f32_e32 v235, v76, v202
	v_mul_f32_e32 v236, v72, v202
	v_mul_f32_e32 v237, v68, v202
	v_mul_f32_e32 v238, v64, v202
	v_cvt_pk_bf16_f32 v224, v235, v236
	v_cvt_pk_bf16_f32 v225, v237, v238
	s_mul_i32 s0, s18, 0x30
	s_add_u32 s72, s70, s0
	s_addc_u32 s73, s71, 0
	global_store_dwordx2 v234, v[224:225], s[72:73]
	v_mul_f32_e32 v235, v77, v203
	v_mul_f32_e32 v236, v73, v203
	v_mul_f32_e32 v237, v69, v203
	v_mul_f32_e32 v238, v65, v203
	v_cvt_pk_bf16_f32 v226, v235, v236
	v_cvt_pk_bf16_f32 v227, v237, v238
	s_mul_i32 s0, s18, 0x31
	s_add_u32 s74, s70, s0
	s_addc_u32 s75, s71, 0
	global_store_dwordx2 v234, v[226:227], s[74:75]
	v_mul_f32_e32 v235, v78, v204
	v_mul_f32_e32 v236, v74, v204
	v_mul_f32_e32 v237, v70, v204
	v_mul_f32_e32 v238, v66, v204
	v_cvt_pk_bf16_f32 v228, v235, v236
; __device__ __forceinline__ unsigned cvt_pk_bf16(float lo, float hi) { unsigned r; asm("v_cvt_pk_bf16_f32 %0, %1, %2" : "=v"(r) : "v"(lo), "v"(hi)); return r; }
;     __device__ __forceinline__ void operator()(const f32x4 (&acc)[2][2][4][2], const Unit& u, int wr, int wc, int fr, int fq, LAS unsigned char* xs, int wid, int lane) const {
;     ...
;         if (mode == 0) {
; #pragma unroll
;             for (int ai = 0; ai < 2; ++ai)
; #pragma unroll
;                 for (int m = 0; m < 4; ++m) {
;                     const float r = rs[ai][m];
;                     bf16_t* rowp = base + (size_t)(row0 + ai * 128 + m * 16 + fr) * ldc + wc * 32 + 8 * fq;
; #pragma unroll
;                     for (int bj = 0; bj < 2; ++bj) { const f32x4 v0 = acc[ai][bj][m][0] * r, v1 = acc[ai][bj][m][1] * r;
;                         u32x4 w; w.x = cvt_pk_bf16(v0[0], v0[1]); w.y = cvt_pk_bf16(v0[2], v0[3]); w.z = cvt_pk_bf16(v1[0], v1[1]); w.w = cvt_pk_bf16(v1[2], v1[3]);
;                         *(u32x4*)(rowp + bj * 128) = w; }
;                     __builtin_amdgcn_sched_barrier(0);
;                 }
	v_cvt_pk_bf16_f32 v229, v237, v238
	s_mul_i32 s0, s18, 0x32
	s_add_u32 s72, s70, s0
	s_addc_u32 s73, s71, 0
	global_store_dwordx2 v234, v[228:229], s[72:73]
	v_mul_f32_e32 v235, v79, v205
	v_mul_f32_e32 v236, v75, v205
	v_mul_f32_e32 v237, v71, v205
	v_mul_f32_e32 v238, v67, v205
	v_cvt_pk_bf16_f32 v230, v235, v236
	v_cvt_pk_bf16_f32 v231, v237, v238
	s_mul_i32 s0, s18, 0x33
	s_add_u32 s74, s70, s0
	s_addc_u32 s75, s71, 0
	global_store_dwordx2 v234, v[230:231], s[74:75]
	v_mul_f32_e32 v235, v60, v206
	v_mul_f32_e32 v236, v56, v206
	v_mul_f32_e32 v237, v52, v206
	v_mul_f32_e32 v238, v48, v206
	v_cvt_pk_bf16_f32 v224, v235, v236
	v_cvt_pk_bf16_f32 v225, v237, v238
	s_mul_i32 s0, s18, 0x80
	s_add_u32 s72, s70, s0
	s_addc_u32 s73, s71, 0
	global_store_dwordx2 v234, v[224:225], s[72:73]
	v_mul_f32_e32 v235, v61, v207
	v_mul_f32_e32 v236, v57, v207
	v_mul_f32_e32 v237, v53, v207
	v_mul_f32_e32 v238, v49, v207
	v_cvt_pk_bf16_f32 v226, v235, v236
	v_cvt_pk_bf16_f32 v227, v237, v238
	s_mul_i32 s0, s18, 0x81
	s_add_u32 s74, s70, s0
	s_addc_u32 s75, s71, 0
	global_store_dwordx2 v234, v[226:227], s[74:75]
	v_mul_f32_e32 v235, v62, v208
	v_mul_f32_e32 v236, v58, v208
	v_mul_f32_e32 v237, v54, v208
	v_mul_f32_e32 v238, v50, v208
	v_cvt_pk_bf16_f32 v228, v235, v236
	v_cvt_pk_bf16_f32 v229, v237, v238
	s_mul_i32 s0, s18, 0x82
	s_add_u32 s72, s70, s0
	s_addc_u32 s73, s71, 0
	global_store_dwordx2 v234, v[228:229], s[72:73]
	v_mul_f32_e32 v235, v63, v209
	v_mul_f32_e32 v236, v59, v209
	v_mul_f32_e32 v237, v55, v209
	v_mul_f32_e32 v238, v51, v209
	v_cvt_pk_bf16_f32 v230, v235, v236
	v_cvt_pk_bf16_f32 v231, v237, v238
	s_mul_i32 s0, s18, 0x83
	s_add_u32 s74, s70, s0
	s_addc_u32 s75, s71, 0
	global_store_dwordx2 v234, v[230:231], s[74:75]
	v_mul_f32_e32 v235, v44, v210
	v_mul_f32_e32 v236, v40, v210
	v_mul_f32_e32 v237, v36, v210
	v_mul_f32_e32 v238, v32, v210
	v_cvt_pk_bf16_f32 v224, v235, v236
	v_cvt_pk_bf16_f32 v225, v237, v238
	s_mul_i32 s0, s18, 0x90
	s_add_u32 s72, s70, s0
	s_addc_u32 s73, s71, 0
	global_store_dwordx2 v234, v[224:225], s[72:73]
	v_mul_f32_e32 v235, v45, v211
	v_mul_f32_e32 v236, v41, v211
	v_mul_f32_e32 v237, v37, v211
	v_mul_f32_e32 v238, v33, v211
	v_cvt_pk_bf16_f32 v226, v235, v236
	v_cvt_pk_bf16_f32 v227, v237, v238
	s_mul_i32 s0, s18, 0x91
	s_add_u32 s74, s70, s0
	s_addc_u32 s75, s71, 0
	global_store_dwordx2 v234, v[226:227], s[74:75]
	v_mul_f32_e32 v235, v46, v212
	v_mul_f32_e32 v236, v42, v212
	v_mul_f32_e32 v237, v38, v212
	v_mul_f32_e32 v238, v34, v212
	v_cvt_pk_bf16_f32 v228, v235, v236
	v_cvt_pk_bf16_f32 v229, v237, v238
	s_mul_i32 s0, s18, 0x92
	s_add_u32 s72, s70, s0
	s_addc_u32 s73, s71, 0
	global_store_dwordx2 v234, v[228:229], s[72:73]
	v_mul_f32_e32 v235, v47, v213
	v_mul_f32_e32 v236, v43, v213
	v_mul_f32_e32 v237, v39, v213
	v_mul_f32_e32 v238, v35, v213
	v_cvt_pk_bf16_f32 v230, v235, v236
	v_cvt_pk_bf16_f32 v231, v237, v238
	s_mul_i32 s0, s18, 0x93
	s_add_u32 s74, s70, s0
	s_addc_u32 s75, s71, 0
	global_store_dwordx2 v234, v[230:231], s[74:75]
	v_mul_f32_e32 v235, v28, v214
	v_mul_f32_e32 v236, v24, v214
	v_mul_f32_e32 v237, v20, v214
	v_mul_f32_e32 v238, v16, v214
	v_cvt_pk_bf16_f32 v224, v235, v236
	v_cvt_pk_bf16_f32 v225, v237, v238
	s_mul_i32 s0, s18, 0xa0
	s_add_u32 s72, s70, s0
	s_addc_u32 s73, s71, 0
	global_store_dwordx2 v234, v[224:225], s[72:73]
	v_mul_f32_e32 v235, v29, v215
	v_mul_f32_e32 v236, v25, v215
	v_mul_f32_e32 v237, v21, v215
	v_mul_f32_e32 v238, v17, v215
	v_cvt_pk_bf16_f32 v226, v235, v236
	v_cvt_pk_bf16_f32 v227, v237, v238
	s_mul_i32 s0, s18, 0xa1
	s_add_u32 s74, s70, s0
	s_addc_u32 s75, s71, 0
	global_store_dwordx2 v234, v[226:227], s[74:75]
	v_mul_f32_e32 v235, v30, v216
	v_mul_f32_e32 v236, v26, v216
	v_mul_f32_e32 v237, v22, v216
	v_mul_f32_e32 v238, v18, v216
	v_cvt_pk_bf16_f32 v228, v235, v236
	v_cvt_pk_bf16_f32 v229, v237, v238
	s_mul_i32 s0, s18, 0xa2
	s_add_u32 s72, s70, s0
	s_addc_u32 s73, s71, 0
	global_store_dwordx2 v234, v[228:229], s[72:73]
	v_mul_f32_e32 v235, v31, v217
	v_mul_f32_e32 v236, v27, v217
	v_mul_f32_e32 v237, v23, v217
	v_mul_f32_e32 v238, v19, v217
	v_cvt_pk_bf16_f32 v230, v235, v236
	v_cvt_pk_bf16_f32 v231, v237, v238
	s_mul_i32 s0, s18, 0xa3
	s_add_u32 s74, s70, s0
	s_addc_u32 s75, s71, 0
	global_store_dwordx2 v234, v[230:231], s[74:75]
	v_mul_f32_e32 v235, v12, v218
	v_mul_f32_e32 v236, v8, v218
	v_mul_f32_e32 v237, v4, v218
	v_mul_f32_e32 v238, v0, v218
	v_cvt_pk_bf16_f32 v224, v235, v236
	v_cvt_pk_bf16_f32 v225, v237, v238
	s_mul_i32 s0, s18, 0xb0
	s_add_u32 s72, s70, s0
	s_addc_u32 s73, s71, 0
	global_store_dwordx2 v234, v[224:225], s[72:73]
	v_mul_f32_e32 v235, v13, v219
	v_mul_f32_e32 v236, v9, v219
	v_mul_f32_e32 v237, v5, v219
	v_mul_f32_e32 v238, v1, v219
	v_cvt_pk_bf16_f32 v226, v235, v236
	v_cvt_pk_bf16_f32 v227, v237, v238
	s_mul_i32 s0, s18, 0xb1
	s_add_u32 s74, s70, s0
	s_addc_u32 s75, s71, 0
	global_store_dwordx2 v234, v[226:227], s[74:75]
	v_mul_f32_e32 v235, v14, v220
	v_mul_f32_e32 v236, v10, v220
	v_mul_f32_e32 v237, v6, v220
	v_mul_f32_e32 v238, v2, v220
	v_cvt_pk_bf16_f32 v228, v235, v236
	v_cvt_pk_bf16_f32 v229, v237, v238
	s_mul_i32 s0, s18, 0xb2
	s_add_u32 s72, s70, s0
	s_addc_u32 s73, s71, 0
	global_store_dwordx2 v234, v[228:229], s[72:73]
	v_mul_f32_e32 v235, v15, v221
	v_mul_f32_e32 v236, v11, v221
	v_mul_f32_e32 v237, v7, v221
	v_mul_f32_e32 v238, v3, v221
	v_cvt_pk_bf16_f32 v230, v235, v236
	v_cvt_pk_bf16_f32 v231, v237, v238
	s_mul_i32 s0, s18, 0xb3
	s_add_u32 s74, s70, s0
	s_addc_u32 s75, s71, 0
	global_store_dwordx2 v234, v[230:231], s[74:75]
	s_andn2_b64 vcc, exec, s[8:9]
	s_mov_b64 s[8:9], -1
	s_cbranch_vccnz .LBB0_959
